# streamed GEMM units: accumulator zeroing removed, first K-loop iteration peeled with SrcC=0 on first-touch MFMAs
# speedup vs baseline: 1.0063x; 1.0042x over previous
.LBB0_166:
	s_ashr_i32 s15, s14, 31
	s_lshl_b64 s[40:41], s[14:15], 19
	s_add_u32 s40, s38, s40
	s_addc_u32 s41, s39, s41
	s_and_b64 s[44:45], s[42:43], exec
	s_cselect_b32 s15, s41, s61
	s_cselect_b32 s78, s40, s60
	s_ashr_i32 s11, s10, 31
	s_lshl_b64 s[44:45], s[10:11], 19
	v_readlane_b32 s74, v253, 51
	v_readlane_b32 s75, v253, 52
	s_add_u32 s44, s74, s44
	s_addc_u32 s45, s75, s45
	s_and_b64 s[74:75], s[42:43], exec
	s_cselect_b32 s11, s45, s73
	s_cselect_b32 s79, s44, s72
	s_add_u32 s60, s60, 0x40080
	s_addc_u32 s61, s61, 0
	s_add_u32 s96, s72, 0x100
	s_addc_u32 s97, s73, 0
	s_mov_b32 vcc_lo, -2
	s_add_u32 s72, s60, 0xfffc0080
	s_addc_u32 s73, s61, -1
	s_add_i32 s76, 16, 0x10000
	s_cmp_eq_u32 vcc_lo, 12
	s_cselect_b32 s75, s15, s73
	s_cselect_b32 s74, s78, s72
	v_add_u32_e32 v150, s76, v80
	s_cselect_b32 s73, s11, s97
	s_cselect_b32 s72, s79, s96
	s_add_i32 vcc_hi, 16, 0x14000
	ds_read_b128 v[142:145], v150
	ds_read_b128 v[146:149], v150 offset:1024
	ds_read_b128 v[160:163], v150 offset:2048
	ds_read_b128 v[166:169], v150 offset:3072
	v_add_u32_e32 v150, vcc_hi, v80
	ds_read_b128 v[170:173], v150
	ds_read_b128 v[174:177], v150 offset:1024
	ds_read_b128 v[178:181], v150 offset:2048
	ds_read_b128 v[182:185], v150 offset:3072
	v_lshl_add_u64 v[150:151], s[60:61], 0, v[138:139]
	s_add_i32 m0, s13, 0xc000
	ds_read_b128 v[186:189], v164
	ds_read_b128 v[204:207], v164 offset:1024
	ds_read_b128 v[214:217], v164 offset:2048
	ds_read_b128 v[218:221], v164 offset:3072
	ds_read_b128 v[222:225], v164 offset:4096
	ds_read_b128 v[226:229], v164 offset:5120
	ds_read_b128 v[230:233], v164 offset:6144
	ds_read_b128 v[234:237], v164 offset:7168
	global_load_lds_dwordx4 v[150:151], off
	v_lshl_add_u64 v[150:151], s[60:61], 0, v[140:141]
	s_add_i32 m0, s13, 0xe000
	s_nop 0
	global_load_lds_dwordx4 v[150:151], off
	s_waitcnt vmcnt(8)
	s_waitcnt lgkmcnt(0)
	s_barrier
	s_waitcnt lgkmcnt(0)
	v_mfma_f32_16x16x32_bf16 v[126:129], v[142:145], v[186:189], 0
	v_mfma_f32_16x16x32_bf16 v[122:125], v[160:163], v[186:189], 0
	v_mfma_f32_16x16x32_bf16 v[110:113], v[142:145], v[214:217], 0
	v_mfma_f32_16x16x32_bf16 v[106:109], v[160:163], v[214:217], 0
	v_mfma_f32_16x16x32_bf16 v[94:97], v[142:145], v[222:225], 0
	v_mfma_f32_16x16x32_bf16 v[90:93], v[160:163], v[222:225], 0
	v_mfma_f32_16x16x32_bf16 v[76:79], v[142:145], v[230:233], 0
	v_mfma_f32_16x16x32_bf16 v[72:75], v[160:163], v[230:233], 0
	v_mfma_f32_16x16x32_bf16 v[126:129], v[146:149], v[204:207], v[126:129]
	v_mfma_f32_16x16x32_bf16 v[122:125], v[166:169], v[204:207], v[122:125]
	v_mfma_f32_16x16x32_bf16 v[110:113], v[146:149], v[218:221], v[110:113]
	v_mfma_f32_16x16x32_bf16 v[106:109], v[166:169], v[218:221], v[106:109]
	v_mfma_f32_16x16x32_bf16 v[94:97], v[146:149], v[226:229], v[94:97]
	v_mfma_f32_16x16x32_bf16 v[90:93], v[166:169], v[226:229], v[90:93]
	v_mfma_f32_16x16x32_bf16 v[76:79], v[146:149], v[234:237], v[76:79]
	v_mfma_f32_16x16x32_bf16 v[72:75], v[166:169], v[234:237], v[72:75]
	v_mfma_f32_16x16x32_bf16 v[118:121], v[170:173], v[186:189], 0
	v_mfma_f32_16x16x32_bf16 v[114:117], v[178:181], v[186:189], 0
	v_mfma_f32_16x16x32_bf16 v[102:105], v[170:173], v[214:217], 0
	v_mfma_f32_16x16x32_bf16 v[98:101], v[178:181], v[214:217], 0
	v_mfma_f32_16x16x32_bf16 v[86:89], v[170:173], v[222:225], 0
	v_mfma_f32_16x16x32_bf16 v[82:85], v[178:181], v[222:225], 0
	v_mfma_f32_16x16x32_bf16 v[68:71], v[170:173], v[230:233], 0
	v_mfma_f32_16x16x32_bf16 v[64:67], v[178:181], v[230:233], 0
	v_mfma_f32_16x16x32_bf16 v[118:121], v[174:177], v[204:207], v[118:121]
	v_mfma_f32_16x16x32_bf16 v[114:117], v[182:185], v[204:207], v[114:117]
	v_mfma_f32_16x16x32_bf16 v[102:105], v[174:177], v[218:221], v[102:105]
	v_mfma_f32_16x16x32_bf16 v[98:101], v[182:185], v[218:221], v[98:101]
	v_mfma_f32_16x16x32_bf16 v[86:89], v[174:177], v[226:229], v[86:89]
	v_mfma_f32_16x16x32_bf16 v[82:85], v[182:185], v[226:229], v[82:85]
	v_mfma_f32_16x16x32_bf16 v[68:71], v[174:177], v[234:237], v[68:71]
	v_mfma_f32_16x16x32_bf16 v[64:67], v[182:185], v[234:237], v[64:67]
	s_barrier
	s_add_i32 s76, s76, s4
	v_lshl_add_u64 v[150:151], s[72:73], 0, v[134:135]
	s_mov_b32 m0, s76
	ds_read_b128 v[186:189], v164 offset:16384
	ds_read_b128 v[204:207], v164 offset:17408
	ds_read_b128 v[214:217], v164 offset:18432
	ds_read_b128 v[218:221], v164 offset:19456
	ds_read_b128 v[222:225], v164 offset:20480
	ds_read_b128 v[226:229], v164 offset:21504
	ds_read_b128 v[230:233], v164 offset:22528
	ds_read_b128 v[234:237], v164 offset:23552
	global_load_lds_dwordx4 v[150:151], off
	s_add_i32 m0, s76, 0x2000
	s_add_u32 s76, s72, 0x40000
	v_lshl_add_u64 v[190:191], s[72:73], 0, v[130:131]
	s_addc_u32 s77, s73, 0
	s_add_i32 vcc_hi, vcc_hi, s4
	global_load_lds_dwordx4 v[190:191], off
	v_lshl_add_u64 v[208:209], s[76:77], 0, v[134:135]
	s_mov_b32 m0, vcc_hi
	v_lshl_add_u64 v[238:239], s[74:75], 0, v[132:133]
	global_load_lds_dwordx4 v[208:209], off
	v_lshl_add_u64 v[208:209], s[76:77], 0, v[130:131]
	s_add_i32 m0, vcc_hi, 0x2000
	s_nop 0
	global_load_lds_dwordx4 v[208:209], off
	v_lshl_add_u64 v[208:209], s[74:75], 0, v[136:137]
	s_mov_b32 m0, s13
	s_nop 0
	global_load_lds_dwordx4 v[208:209], off
	s_mov_b32 m0, s25
	s_nop 0
	global_load_lds_dwordx4 v[238:239], off
	s_waitcnt vmcnt(8)
	s_waitcnt lgkmcnt(0)
	s_barrier
	s_waitcnt lgkmcnt(0)
	v_mfma_f32_16x16x32_bf16 v[60:63], v[142:145], v[186:189], 0
	v_mfma_f32_16x16x32_bf16 v[56:59], v[160:163], v[186:189], 0
	v_mfma_f32_16x16x32_bf16 v[44:47], v[142:145], v[214:217], 0
	v_mfma_f32_16x16x32_bf16 v[40:43], v[160:163], v[214:217], 0
	v_mfma_f32_16x16x32_bf16 v[28:31], v[142:145], v[222:225], 0
	v_mfma_f32_16x16x32_bf16 v[24:27], v[160:163], v[222:225], 0
	v_mfma_f32_16x16x32_bf16 v[12:15], v[142:145], v[230:233], 0
	v_mfma_f32_16x16x32_bf16 v[8:11], v[160:163], v[230:233], 0
	v_mfma_f32_16x16x32_bf16 v[60:63], v[146:149], v[204:207], v[60:63]
	v_mfma_f32_16x16x32_bf16 v[56:59], v[166:169], v[204:207], v[56:59]
	v_mfma_f32_16x16x32_bf16 v[44:47], v[146:149], v[218:221], v[44:47]
	v_mfma_f32_16x16x32_bf16 v[40:43], v[166:169], v[218:221], v[40:43]
	v_mfma_f32_16x16x32_bf16 v[28:31], v[146:149], v[226:229], v[28:31]
	v_mfma_f32_16x16x32_bf16 v[24:27], v[166:169], v[226:229], v[24:27]
	v_mfma_f32_16x16x32_bf16 v[12:15], v[146:149], v[234:237], v[12:15]
	v_mfma_f32_16x16x32_bf16 v[8:11], v[166:169], v[234:237], v[8:11]
	v_mfma_f32_16x16x32_bf16 v[52:55], v[170:173], v[186:189], 0
	v_mfma_f32_16x16x32_bf16 v[48:51], v[178:181], v[186:189], 0
	v_mfma_f32_16x16x32_bf16 v[36:39], v[170:173], v[214:217], 0
	v_mfma_f32_16x16x32_bf16 v[32:35], v[178:181], v[214:217], 0
	v_mfma_f32_16x16x32_bf16 v[20:23], v[170:173], v[222:225], 0
	v_mfma_f32_16x16x32_bf16 v[16:19], v[178:181], v[222:225], 0
	v_mfma_f32_16x16x32_bf16 v[4:7], v[170:173], v[230:233], 0
	v_mfma_f32_16x16x32_bf16 v[0:3], v[178:181], v[230:233], 0
	v_mfma_f32_16x16x32_bf16 v[52:55], v[174:177], v[204:207], v[52:55]
	v_mfma_f32_16x16x32_bf16 v[48:51], v[182:185], v[204:207], v[48:51]
	v_mfma_f32_16x16x32_bf16 v[36:39], v[174:177], v[218:221], v[36:39]
	v_mfma_f32_16x16x32_bf16 v[32:35], v[182:185], v[218:221], v[32:35]
	v_mfma_f32_16x16x32_bf16 v[20:23], v[174:177], v[226:229], v[20:23]
	v_mfma_f32_16x16x32_bf16 v[16:19], v[182:185], v[226:229], v[16:19]
	v_mfma_f32_16x16x32_bf16 v[4:7], v[174:177], v[234:237], v[4:7]
	v_mfma_f32_16x16x32_bf16 v[0:3], v[182:185], v[234:237], v[0:3]
	s_barrier
	s_add_i32 s76, 16, 0x18000
	v_add_u32_e32 v165, s76, v80
	s_add_i32 s77, 16, 0x1c000
	ds_read_b128 v[142:145], v165
	ds_read_b128 v[146:149], v165 offset:1024
	ds_read_b128 v[160:163], v165 offset:2048
	ds_read_b128 v[166:169], v165 offset:3072
	v_add_u32_e32 v165, s77, v80
	ds_read_b128 v[170:173], v165
	ds_read_b128 v[174:177], v165 offset:1024
	ds_read_b128 v[178:181], v165 offset:2048
	ds_read_b128 v[182:185], v165 offset:3072
	s_add_u32 s74, s74, 0x40000
	s_addc_u32 s75, s75, 0
	s_mov_b32 m0, s30
	v_lshl_add_u64 v[240:241], s[74:75], 0, v[136:137]
	ds_read_b128 v[186:189], v164 offset:32768
	ds_read_b128 v[204:207], v164 offset:33792
	ds_read_b128 v[214:217], v164 offset:34816
	ds_read_b128 v[218:221], v164 offset:35840
	ds_read_b128 v[222:225], v164 offset:36864
	ds_read_b128 v[226:229], v164 offset:37888
	ds_read_b128 v[230:233], v164 offset:38912
	ds_read_b128 v[234:237], v164 offset:39936
	global_load_lds_dwordx4 v[240:241], off
	v_lshl_add_u64 v[240:241], s[74:75], 0, v[132:133]
	s_mov_b32 m0, s33
	s_nop 0
	global_load_lds_dwordx4 v[240:241], off
	s_waitcnt vmcnt(8)
	s_waitcnt lgkmcnt(0)
	s_barrier
	s_waitcnt lgkmcnt(0)
	v_mfma_f32_16x16x32_bf16 v[126:129], v[142:145], v[186:189], v[126:129]
	v_mfma_f32_16x16x32_bf16 v[122:125], v[160:163], v[186:189], v[122:125]
	v_mfma_f32_16x16x32_bf16 v[110:113], v[142:145], v[214:217], v[110:113]
	v_mfma_f32_16x16x32_bf16 v[106:109], v[160:163], v[214:217], v[106:109]
	v_mfma_f32_16x16x32_bf16 v[94:97], v[142:145], v[222:225], v[94:97]
	v_mfma_f32_16x16x32_bf16 v[90:93], v[160:163], v[222:225], v[90:93]
	v_mfma_f32_16x16x32_bf16 v[76:79], v[142:145], v[230:233], v[76:79]
	v_mfma_f32_16x16x32_bf16 v[72:75], v[160:163], v[230:233], v[72:75]
	v_mfma_f32_16x16x32_bf16 v[126:129], v[146:149], v[204:207], v[126:129]
	v_mfma_f32_16x16x32_bf16 v[122:125], v[166:169], v[204:207], v[122:125]
	v_mfma_f32_16x16x32_bf16 v[110:113], v[146:149], v[218:221], v[110:113]
	v_mfma_f32_16x16x32_bf16 v[106:109], v[166:169], v[218:221], v[106:109]
	v_mfma_f32_16x16x32_bf16 v[94:97], v[146:149], v[226:229], v[94:97]
	v_mfma_f32_16x16x32_bf16 v[90:93], v[166:169], v[226:229], v[90:93]
	v_mfma_f32_16x16x32_bf16 v[76:79], v[146:149], v[234:237], v[76:79]
	v_mfma_f32_16x16x32_bf16 v[72:75], v[166:169], v[234:237], v[72:75]
	v_mfma_f32_16x16x32_bf16 v[118:121], v[170:173], v[186:189], v[118:121]
	v_mfma_f32_16x16x32_bf16 v[114:117], v[178:181], v[186:189], v[114:117]
	v_mfma_f32_16x16x32_bf16 v[102:105], v[170:173], v[214:217], v[102:105]
	v_mfma_f32_16x16x32_bf16 v[98:101], v[178:181], v[214:217], v[98:101]
	v_mfma_f32_16x16x32_bf16 v[86:89], v[170:173], v[222:225], v[86:89]
	v_mfma_f32_16x16x32_bf16 v[82:85], v[178:181], v[222:225], v[82:85]
	v_mfma_f32_16x16x32_bf16 v[68:71], v[170:173], v[230:233], v[68:71]
	v_mfma_f32_16x16x32_bf16 v[64:67], v[178:181], v[230:233], v[64:67]
	v_mfma_f32_16x16x32_bf16 v[118:121], v[174:177], v[204:207], v[118:121]
	v_mfma_f32_16x16x32_bf16 v[114:117], v[182:185], v[204:207], v[114:117]
	v_mfma_f32_16x16x32_bf16 v[102:105], v[174:177], v[218:221], v[102:105]
	v_mfma_f32_16x16x32_bf16 v[98:101], v[182:185], v[218:221], v[98:101]
	v_mfma_f32_16x16x32_bf16 v[86:89], v[174:177], v[226:229], v[86:89]
	v_mfma_f32_16x16x32_bf16 v[82:85], v[182:185], v[226:229], v[82:85]
	v_mfma_f32_16x16x32_bf16 v[68:71], v[174:177], v[234:237], v[68:71]
	v_mfma_f32_16x16x32_bf16 v[64:67], v[182:185], v[234:237], v[64:67]
	s_barrier
	s_add_i32 s74, s76, s4
	v_lshl_add_u64 v[150:151], v[150:151], 0, s[20:21]
	s_mov_b32 m0, s74
	ds_read_b128 v[186:189], v164 offset:49152
	ds_read_b128 v[204:207], v164 offset:50176
	ds_read_b128 v[214:217], v164 offset:51200
	ds_read_b128 v[218:221], v164 offset:52224
	ds_read_b128 v[222:225], v164 offset:53248
	ds_read_b128 v[226:229], v164 offset:54272
	ds_read_b128 v[230:233], v164 offset:55296
	ds_read_b128 v[234:237], v164 offset:56320
	global_load_lds_dwordx4 v[150:151], off
	s_add_i32 m0, s74, 0x2000
	s_add_u32 s72, s72, 0x40080
	v_lshl_add_u64 v[150:151], v[190:191], 0, s[20:21]
	s_addc_u32 s73, s73, 0
	s_add_i32 s74, s77, s4
	global_load_lds_dwordx4 v[150:151], off
	v_lshl_add_u64 v[150:151], s[72:73], 0, v[134:135]
	s_mov_b32 m0, s74
	s_nop 0
	global_load_lds_dwordx4 v[150:151], off
	v_lshl_add_u64 v[150:151], s[72:73], 0, v[130:131]
	s_add_i32 m0, s74, 0x2000
	s_nop 0
	global_load_lds_dwordx4 v[150:151], off
	v_lshl_add_u64 v[150:151], v[208:209], 0, s[20:21]
	s_mov_b32 m0, s34
	s_nop 0
	global_load_lds_dwordx4 v[150:151], off
	v_lshl_add_u64 v[150:151], v[238:239], 0, s[20:21]
	s_mov_b32 m0, s36
	s_nop 0
	global_load_lds_dwordx4 v[150:151], off
	s_waitcnt vmcnt(8)
	s_waitcnt lgkmcnt(0)
	s_barrier
	s_waitcnt lgkmcnt(0)
	v_mfma_f32_16x16x32_bf16 v[60:63], v[142:145], v[186:189], v[60:63]
	v_mfma_f32_16x16x32_bf16 v[56:59], v[160:163], v[186:189], v[56:59]
	v_mfma_f32_16x16x32_bf16 v[44:47], v[142:145], v[214:217], v[44:47]
	v_mfma_f32_16x16x32_bf16 v[40:43], v[160:163], v[214:217], v[40:43]
	v_mfma_f32_16x16x32_bf16 v[28:31], v[142:145], v[222:225], v[28:31]
	v_mfma_f32_16x16x32_bf16 v[24:27], v[160:163], v[222:225], v[24:27]
	v_mfma_f32_16x16x32_bf16 v[12:15], v[142:145], v[230:233], v[12:15]
	v_mfma_f32_16x16x32_bf16 v[8:11], v[160:163], v[230:233], v[8:11]
	v_mfma_f32_16x16x32_bf16 v[60:63], v[146:149], v[204:207], v[60:63]
	v_mfma_f32_16x16x32_bf16 v[56:59], v[166:169], v[204:207], v[56:59]
	v_mfma_f32_16x16x32_bf16 v[44:47], v[146:149], v[218:221], v[44:47]
	v_mfma_f32_16x16x32_bf16 v[40:43], v[166:169], v[218:221], v[40:43]
	v_mfma_f32_16x16x32_bf16 v[28:31], v[146:149], v[226:229], v[28:31]
	v_mfma_f32_16x16x32_bf16 v[24:27], v[166:169], v[226:229], v[24:27]
	v_mfma_f32_16x16x32_bf16 v[12:15], v[146:149], v[234:237], v[12:15]
	v_mfma_f32_16x16x32_bf16 v[8:11], v[166:169], v[234:237], v[8:11]
	v_mfma_f32_16x16x32_bf16 v[52:55], v[170:173], v[186:189], v[52:55]
	v_mfma_f32_16x16x32_bf16 v[48:51], v[178:181], v[186:189], v[48:51]
	v_mfma_f32_16x16x32_bf16 v[36:39], v[170:173], v[214:217], v[36:39]
	v_mfma_f32_16x16x32_bf16 v[32:35], v[178:181], v[214:217], v[32:35]
	v_mfma_f32_16x16x32_bf16 v[20:23], v[170:173], v[222:225], v[20:23]
	v_mfma_f32_16x16x32_bf16 v[16:19], v[178:181], v[222:225], v[16:19]
	v_mfma_f32_16x16x32_bf16 v[4:7], v[170:173], v[230:233], v[4:7]
	v_mfma_f32_16x16x32_bf16 v[0:3], v[178:181], v[230:233], v[0:3]
	v_mfma_f32_16x16x32_bf16 v[52:55], v[174:177], v[204:207], v[52:55]
	v_mfma_f32_16x16x32_bf16 v[48:51], v[182:185], v[204:207], v[48:51]
	v_mfma_f32_16x16x32_bf16 v[36:39], v[174:177], v[218:221], v[36:39]
	v_mfma_f32_16x16x32_bf16 v[32:35], v[182:185], v[218:221], v[32:35]
	v_mfma_f32_16x16x32_bf16 v[20:23], v[174:177], v[226:229], v[20:23]
	v_mfma_f32_16x16x32_bf16 v[16:19], v[182:185], v[226:229], v[16:19]
	v_mfma_f32_16x16x32_bf16 v[4:7], v[174:177], v[234:237], v[4:7]
	v_mfma_f32_16x16x32_bf16 v[0:3], v[182:185], v[234:237], v[0:3]
	s_barrier
	s_add_i32 vcc_lo, vcc_lo, 2
	s_add_u32 s60, s60, 0x100
	s_addc_u32 s61, s61, 0
	s_add_u32 s96, s96, 0x100
	s_addc_u32 s97, s97, 0
	s_cmp_gt_u32 vcc_lo, 13

.LBB0_192:
	s_add_u32 s74, s54, 0x100
	s_addc_u32 s75, s55, 0
	s_mov_b32 s78, -2
	s_waitcnt lgkmcnt(0)
	s_add_u32 s44, s40, 0x100
	s_addc_u32 s45, s41, 0
	s_add_i32 s76, 16, 0x10000
	s_cmp_eq_u32 s78, 40
	s_cselect_b32 s61, s11, s45
	s_cselect_b32 s60, s10, s44
	v_add_u32_e32 v80, s76, v144
	s_cselect_b32 s55, s15, s75
	s_cselect_b32 s54, s14, s74
	s_add_i32 s77, 16, 0x14000
	ds_read_b128 v[146:149], v80
	ds_read_b128 v[160:163], v80 offset:1024
	ds_read_b128 v[164:167], v80 offset:2048
	ds_read_b128 v[168:171], v80 offset:3072
	v_add_u32_e32 v80, s77, v144
	ds_read_b128 v[172:175], v80
	ds_read_b128 v[176:179], v80 offset:1024
	ds_read_b128 v[180:183], v80 offset:2048
	ds_read_b128 v[184:187], v80 offset:3072
	v_lshl_add_u64 v[142:143], s[40:41], 0, v[138:139]
	s_add_i32 m0, s13, 0xc000
	ds_read_b128 v[188:191], v145
	ds_read_b128 v[204:207], v145 offset:1024
	ds_read_b128 v[214:217], v145 offset:2048
	ds_read_b128 v[218:221], v145 offset:3072
	ds_read_b128 v[222:225], v145 offset:4096
	ds_read_b128 v[226:229], v145 offset:5120
	ds_read_b128 v[230:233], v145 offset:6144
	ds_read_b128 v[234:237], v145 offset:7168
	global_load_lds_dwordx4 v[142:143], off
	v_lshl_add_u64 v[142:143], s[40:41], 0, v[140:141]
	s_add_i32 m0, s13, 0xe000
	s_nop 0
	global_load_lds_dwordx4 v[142:143], off
	s_waitcnt vmcnt(8)
	s_waitcnt lgkmcnt(0)
	s_barrier
	s_waitcnt lgkmcnt(0)
	v_mfma_f32_16x16x32_bf16 v[126:129], v[146:149], v[188:191], 0
	v_mfma_f32_16x16x32_bf16 v[122:125], v[164:167], v[188:191], 0
	v_mfma_f32_16x16x32_bf16 v[110:113], v[146:149], v[214:217], 0
	v_mfma_f32_16x16x32_bf16 v[106:109], v[164:167], v[214:217], 0
	v_mfma_f32_16x16x32_bf16 v[94:97], v[146:149], v[222:225], 0
	v_mfma_f32_16x16x32_bf16 v[90:93], v[164:167], v[222:225], 0
	v_mfma_f32_16x16x32_bf16 v[76:79], v[146:149], v[230:233], 0
	v_mfma_f32_16x16x32_bf16 v[72:75], v[164:167], v[230:233], 0
	v_mfma_f32_16x16x32_bf16 v[126:129], v[160:163], v[204:207], v[126:129]
	v_mfma_f32_16x16x32_bf16 v[122:125], v[168:171], v[204:207], v[122:125]
	v_mfma_f32_16x16x32_bf16 v[110:113], v[160:163], v[218:221], v[110:113]
	v_mfma_f32_16x16x32_bf16 v[106:109], v[168:171], v[218:221], v[106:109]
	v_mfma_f32_16x16x32_bf16 v[94:97], v[160:163], v[226:229], v[94:97]
	v_mfma_f32_16x16x32_bf16 v[90:93], v[168:171], v[226:229], v[90:93]
	v_mfma_f32_16x16x32_bf16 v[76:79], v[160:163], v[234:237], v[76:79]
	v_mfma_f32_16x16x32_bf16 v[72:75], v[168:171], v[234:237], v[72:75]
	v_mfma_f32_16x16x32_bf16 v[118:121], v[172:175], v[188:191], 0
	v_mfma_f32_16x16x32_bf16 v[114:117], v[180:183], v[188:191], 0
	v_mfma_f32_16x16x32_bf16 v[102:105], v[172:175], v[214:217], 0
	v_mfma_f32_16x16x32_bf16 v[98:101], v[180:183], v[214:217], 0
	v_mfma_f32_16x16x32_bf16 v[86:89], v[172:175], v[222:225], 0
	v_mfma_f32_16x16x32_bf16 v[82:85], v[180:183], v[222:225], 0
	v_mfma_f32_16x16x32_bf16 v[68:71], v[172:175], v[230:233], 0
	v_mfma_f32_16x16x32_bf16 v[64:67], v[180:183], v[230:233], 0
	v_mfma_f32_16x16x32_bf16 v[118:121], v[176:179], v[204:207], v[118:121]
	v_mfma_f32_16x16x32_bf16 v[114:117], v[184:187], v[204:207], v[114:117]
	v_mfma_f32_16x16x32_bf16 v[102:105], v[176:179], v[218:221], v[102:105]
	v_mfma_f32_16x16x32_bf16 v[98:101], v[184:187], v[218:221], v[98:101]
	v_mfma_f32_16x16x32_bf16 v[86:89], v[176:179], v[226:229], v[86:89]
	v_mfma_f32_16x16x32_bf16 v[82:85], v[184:187], v[226:229], v[82:85]
	v_mfma_f32_16x16x32_bf16 v[68:71], v[176:179], v[234:237], v[68:71]
	v_mfma_f32_16x16x32_bf16 v[64:67], v[184:187], v[234:237], v[64:67]
	s_barrier
	s_add_i32 s40, s76, s4
	v_lshl_add_u64 v[142:143], s[54:55], 0, v[134:135]
	s_mov_b32 m0, s40
	ds_read_b128 v[188:191], v145 offset:16384
	ds_read_b128 v[204:207], v145 offset:17408
	ds_read_b128 v[214:217], v145 offset:18432
	ds_read_b128 v[218:221], v145 offset:19456
	ds_read_b128 v[222:225], v145 offset:20480
	ds_read_b128 v[226:229], v145 offset:21504
	ds_read_b128 v[230:233], v145 offset:22528
	ds_read_b128 v[234:237], v145 offset:23552
	global_load_lds_dwordx4 v[142:143], off
	s_add_i32 m0, s40, 0x2000
	s_add_u32 s40, s54, 0xb0000
	v_lshl_add_u64 v[150:151], s[54:55], 0, v[130:131]
	s_addc_u32 s41, s55, 0
	s_add_i32 s76, s77, s4
	global_load_lds_dwordx4 v[150:151], off
	v_lshl_add_u64 v[208:209], s[40:41], 0, v[134:135]
	s_mov_b32 m0, s76
	v_lshl_add_u64 v[238:239], s[60:61], 0, v[132:133]
	global_load_lds_dwordx4 v[208:209], off
	v_lshl_add_u64 v[208:209], s[40:41], 0, v[130:131]
	s_add_i32 m0, s76, 0x2000
	s_nop 0
	global_load_lds_dwordx4 v[208:209], off
	v_lshl_add_u64 v[208:209], s[60:61], 0, v[136:137]
	s_mov_b32 m0, s13
	s_nop 0
	global_load_lds_dwordx4 v[208:209], off
	s_mov_b32 m0, s25
	s_nop 0
	global_load_lds_dwordx4 v[238:239], off
	s_waitcnt vmcnt(8)
	s_waitcnt lgkmcnt(0)
	s_barrier
	s_waitcnt lgkmcnt(0)
	v_mfma_f32_16x16x32_bf16 v[60:63], v[146:149], v[188:191], 0
	v_mfma_f32_16x16x32_bf16 v[56:59], v[164:167], v[188:191], 0
	v_mfma_f32_16x16x32_bf16 v[44:47], v[146:149], v[214:217], 0
	v_mfma_f32_16x16x32_bf16 v[40:43], v[164:167], v[214:217], 0
	v_mfma_f32_16x16x32_bf16 v[28:31], v[146:149], v[222:225], 0
	v_mfma_f32_16x16x32_bf16 v[24:27], v[164:167], v[222:225], 0
	v_mfma_f32_16x16x32_bf16 v[12:15], v[146:149], v[230:233], 0
	v_mfma_f32_16x16x32_bf16 v[8:11], v[164:167], v[230:233], 0
	v_mfma_f32_16x16x32_bf16 v[60:63], v[160:163], v[204:207], v[60:63]
	v_mfma_f32_16x16x32_bf16 v[56:59], v[168:171], v[204:207], v[56:59]
	v_mfma_f32_16x16x32_bf16 v[44:47], v[160:163], v[218:221], v[44:47]
	v_mfma_f32_16x16x32_bf16 v[40:43], v[168:171], v[218:221], v[40:43]
	v_mfma_f32_16x16x32_bf16 v[28:31], v[160:163], v[226:229], v[28:31]
	v_mfma_f32_16x16x32_bf16 v[24:27], v[168:171], v[226:229], v[24:27]
	v_mfma_f32_16x16x32_bf16 v[12:15], v[160:163], v[234:237], v[12:15]
	v_mfma_f32_16x16x32_bf16 v[8:11], v[168:171], v[234:237], v[8:11]
	v_mfma_f32_16x16x32_bf16 v[52:55], v[172:175], v[188:191], 0
	v_mfma_f32_16x16x32_bf16 v[48:51], v[180:183], v[188:191], 0
	v_mfma_f32_16x16x32_bf16 v[36:39], v[172:175], v[214:217], 0
	v_mfma_f32_16x16x32_bf16 v[32:35], v[180:183], v[214:217], 0
	v_mfma_f32_16x16x32_bf16 v[20:23], v[172:175], v[222:225], 0
	v_mfma_f32_16x16x32_bf16 v[16:19], v[180:183], v[222:225], 0
	v_mfma_f32_16x16x32_bf16 v[4:7], v[172:175], v[230:233], 0
	v_mfma_f32_16x16x32_bf16 v[0:3], v[180:183], v[230:233], 0
	v_mfma_f32_16x16x32_bf16 v[52:55], v[176:179], v[204:207], v[52:55]
	v_mfma_f32_16x16x32_bf16 v[48:51], v[184:187], v[204:207], v[48:51]
	v_mfma_f32_16x16x32_bf16 v[36:39], v[176:179], v[218:221], v[36:39]
	v_mfma_f32_16x16x32_bf16 v[32:35], v[184:187], v[218:221], v[32:35]
	v_mfma_f32_16x16x32_bf16 v[20:23], v[176:179], v[226:229], v[20:23]
	v_mfma_f32_16x16x32_bf16 v[16:19], v[184:187], v[226:229], v[16:19]
	v_mfma_f32_16x16x32_bf16 v[4:7], v[176:179], v[234:237], v[4:7]
	v_mfma_f32_16x16x32_bf16 v[0:3], v[184:187], v[234:237], v[0:3]
	s_barrier
	s_add_i32 s76, 16, 0x18000
	v_add_u32_e32 v80, s76, v144
	s_add_i32 s77, 16, 0x1c000
	ds_read_b128 v[146:149], v80
	ds_read_b128 v[160:163], v80 offset:1024
	ds_read_b128 v[164:167], v80 offset:2048
	ds_read_b128 v[168:171], v80 offset:3072
	v_add_u32_e32 v80, s77, v144
	ds_read_b128 v[172:175], v80
	ds_read_b128 v[176:179], v80 offset:1024
	ds_read_b128 v[180:183], v80 offset:2048
	ds_read_b128 v[184:187], v80 offset:3072
	s_add_u32 s40, s60, 0xb0000
	s_addc_u32 s41, s61, 0
	s_mov_b32 m0, s30
	v_lshl_add_u64 v[240:241], s[40:41], 0, v[136:137]
	ds_read_b128 v[188:191], v145 offset:32768
	ds_read_b128 v[204:207], v145 offset:33792
	ds_read_b128 v[214:217], v145 offset:34816
	ds_read_b128 v[218:221], v145 offset:35840
	ds_read_b128 v[222:225], v145 offset:36864
	ds_read_b128 v[226:229], v145 offset:37888
	ds_read_b128 v[230:233], v145 offset:38912
	ds_read_b128 v[234:237], v145 offset:39936
	global_load_lds_dwordx4 v[240:241], off
	v_lshl_add_u64 v[240:241], s[40:41], 0, v[132:133]
	s_mov_b32 m0, s33
	s_nop 0
	global_load_lds_dwordx4 v[240:241], off
	s_waitcnt vmcnt(8)
	s_waitcnt lgkmcnt(0)
	s_barrier
	s_waitcnt lgkmcnt(0)
	v_mfma_f32_16x16x32_bf16 v[126:129], v[146:149], v[188:191], v[126:129]
	v_mfma_f32_16x16x32_bf16 v[122:125], v[164:167], v[188:191], v[122:125]
	v_mfma_f32_16x16x32_bf16 v[110:113], v[146:149], v[214:217], v[110:113]
	v_mfma_f32_16x16x32_bf16 v[106:109], v[164:167], v[214:217], v[106:109]
	v_mfma_f32_16x16x32_bf16 v[94:97], v[146:149], v[222:225], v[94:97]
	v_mfma_f32_16x16x32_bf16 v[90:93], v[164:167], v[222:225], v[90:93]
	v_mfma_f32_16x16x32_bf16 v[76:79], v[146:149], v[230:233], v[76:79]
	v_mfma_f32_16x16x32_bf16 v[72:75], v[164:167], v[230:233], v[72:75]
	v_mfma_f32_16x16x32_bf16 v[126:129], v[160:163], v[204:207], v[126:129]
	v_mfma_f32_16x16x32_bf16 v[122:125], v[168:171], v[204:207], v[122:125]
	v_mfma_f32_16x16x32_bf16 v[110:113], v[160:163], v[218:221], v[110:113]
	v_mfma_f32_16x16x32_bf16 v[106:109], v[168:171], v[218:221], v[106:109]
	v_mfma_f32_16x16x32_bf16 v[94:97], v[160:163], v[226:229], v[94:97]
	v_mfma_f32_16x16x32_bf16 v[90:93], v[168:171], v[226:229], v[90:93]
	v_mfma_f32_16x16x32_bf16 v[76:79], v[160:163], v[234:237], v[76:79]
	v_mfma_f32_16x16x32_bf16 v[72:75], v[168:171], v[234:237], v[72:75]
	v_mfma_f32_16x16x32_bf16 v[118:121], v[172:175], v[188:191], v[118:121]
	v_mfma_f32_16x16x32_bf16 v[114:117], v[180:183], v[188:191], v[114:117]
	v_mfma_f32_16x16x32_bf16 v[102:105], v[172:175], v[214:217], v[102:105]
	v_mfma_f32_16x16x32_bf16 v[98:101], v[180:183], v[214:217], v[98:101]
	v_mfma_f32_16x16x32_bf16 v[86:89], v[172:175], v[222:225], v[86:89]
	v_mfma_f32_16x16x32_bf16 v[82:85], v[180:183], v[222:225], v[82:85]
	v_mfma_f32_16x16x32_bf16 v[68:71], v[172:175], v[230:233], v[68:71]
	v_mfma_f32_16x16x32_bf16 v[64:67], v[180:183], v[230:233], v[64:67]
	v_mfma_f32_16x16x32_bf16 v[118:121], v[176:179], v[204:207], v[118:121]
	v_mfma_f32_16x16x32_bf16 v[114:117], v[184:187], v[204:207], v[114:117]
	v_mfma_f32_16x16x32_bf16 v[102:105], v[176:179], v[218:221], v[102:105]
	v_mfma_f32_16x16x32_bf16 v[98:101], v[184:187], v[218:221], v[98:101]
	v_mfma_f32_16x16x32_bf16 v[86:89], v[176:179], v[226:229], v[86:89]
	v_mfma_f32_16x16x32_bf16 v[82:85], v[184:187], v[226:229], v[82:85]
	v_mfma_f32_16x16x32_bf16 v[68:71], v[176:179], v[234:237], v[68:71]
	v_mfma_f32_16x16x32_bf16 v[64:67], v[184:187], v[234:237], v[64:67]
	s_barrier
	s_add_i32 s40, s76, s4
	v_lshl_add_u64 v[142:143], v[142:143], 0, s[20:21]
	s_mov_b32 m0, s40
	ds_read_b128 v[188:191], v145 offset:49152
	ds_read_b128 v[204:207], v145 offset:50176
	ds_read_b128 v[214:217], v145 offset:51200
	ds_read_b128 v[218:221], v145 offset:52224
	ds_read_b128 v[222:225], v145 offset:53248
	ds_read_b128 v[226:229], v145 offset:54272
	ds_read_b128 v[230:233], v145 offset:55296
	ds_read_b128 v[234:237], v145 offset:56320
	global_load_lds_dwordx4 v[142:143], off
	s_add_i32 m0, s40, 0x2000
	s_add_u32 s40, s54, 0xb0080
	v_lshl_add_u64 v[142:143], v[150:151], 0, s[20:21]
	s_addc_u32 s41, s55, 0
	s_add_i32 s54, s77, s4
	global_load_lds_dwordx4 v[142:143], off
	v_lshl_add_u64 v[142:143], s[40:41], 0, v[134:135]
	s_mov_b32 m0, s54
	s_nop 0
	global_load_lds_dwordx4 v[142:143], off
	v_lshl_add_u64 v[142:143], s[40:41], 0, v[130:131]
	s_add_i32 m0, s54, 0x2000
	s_nop 0
	global_load_lds_dwordx4 v[142:143], off
	v_lshl_add_u64 v[142:143], v[208:209], 0, s[20:21]
	s_mov_b32 m0, s34
	s_nop 0
	global_load_lds_dwordx4 v[142:143], off
	v_lshl_add_u64 v[142:143], v[238:239], 0, s[20:21]
	s_mov_b32 m0, s36
	s_nop 0
	global_load_lds_dwordx4 v[142:143], off
	s_waitcnt vmcnt(8)
	s_waitcnt lgkmcnt(0)
	s_barrier
	s_waitcnt lgkmcnt(0)
	v_mfma_f32_16x16x32_bf16 v[60:63], v[146:149], v[188:191], v[60:63]
	v_mfma_f32_16x16x32_bf16 v[56:59], v[164:167], v[188:191], v[56:59]
	v_mfma_f32_16x16x32_bf16 v[44:47], v[146:149], v[214:217], v[44:47]
	v_mfma_f32_16x16x32_bf16 v[40:43], v[164:167], v[214:217], v[40:43]
	v_mfma_f32_16x16x32_bf16 v[28:31], v[146:149], v[222:225], v[28:31]
	v_mfma_f32_16x16x32_bf16 v[24:27], v[164:167], v[222:225], v[24:27]
	v_mfma_f32_16x16x32_bf16 v[12:15], v[146:149], v[230:233], v[12:15]
	v_mfma_f32_16x16x32_bf16 v[8:11], v[164:167], v[230:233], v[8:11]
	v_mfma_f32_16x16x32_bf16 v[60:63], v[160:163], v[204:207], v[60:63]
	v_mfma_f32_16x16x32_bf16 v[56:59], v[168:171], v[204:207], v[56:59]
	v_mfma_f32_16x16x32_bf16 v[44:47], v[160:163], v[218:221], v[44:47]
	v_mfma_f32_16x16x32_bf16 v[40:43], v[168:171], v[218:221], v[40:43]
	v_mfma_f32_16x16x32_bf16 v[28:31], v[160:163], v[226:229], v[28:31]
	v_mfma_f32_16x16x32_bf16 v[24:27], v[168:171], v[226:229], v[24:27]
	v_mfma_f32_16x16x32_bf16 v[12:15], v[160:163], v[234:237], v[12:15]
	v_mfma_f32_16x16x32_bf16 v[8:11], v[168:171], v[234:237], v[8:11]
	v_mfma_f32_16x16x32_bf16 v[52:55], v[172:175], v[188:191], v[52:55]
	v_mfma_f32_16x16x32_bf16 v[48:51], v[180:183], v[188:191], v[48:51]
	v_mfma_f32_16x16x32_bf16 v[36:39], v[172:175], v[214:217], v[36:39]
	v_mfma_f32_16x16x32_bf16 v[32:35], v[180:183], v[214:217], v[32:35]
	v_mfma_f32_16x16x32_bf16 v[20:23], v[172:175], v[222:225], v[20:23]
	v_mfma_f32_16x16x32_bf16 v[16:19], v[180:183], v[222:225], v[16:19]
	v_mfma_f32_16x16x32_bf16 v[4:7], v[172:175], v[230:233], v[4:7]
	v_mfma_f32_16x16x32_bf16 v[0:3], v[180:183], v[230:233], v[0:3]
	v_mfma_f32_16x16x32_bf16 v[52:55], v[176:179], v[204:207], v[52:55]
	v_mfma_f32_16x16x32_bf16 v[48:51], v[184:187], v[204:207], v[48:51]
	v_mfma_f32_16x16x32_bf16 v[36:39], v[176:179], v[218:221], v[36:39]
	v_mfma_f32_16x16x32_bf16 v[32:35], v[184:187], v[218:221], v[32:35]
	v_mfma_f32_16x16x32_bf16 v[20:23], v[176:179], v[226:229], v[20:23]
	v_mfma_f32_16x16x32_bf16 v[16:19], v[184:187], v[226:229], v[16:19]
	v_mfma_f32_16x16x32_bf16 v[4:7], v[176:179], v[234:237], v[4:7]
	v_mfma_f32_16x16x32_bf16 v[0:3], v[184:187], v[234:237], v[0:3]
	s_barrier
	s_add_i32 s78, s78, 2
	s_add_u32 s74, s74, 0x100
	s_addc_u32 s75, s75, 0
	s_cmp_gt_u32 s78, 41
	s_mov_b64 s[40:41], s[44:45]

.LBB0_226:
	s_ashr_i32 s15, s14, 31
	s_lshl_b64 s[40:41], s[14:15], 19
	s_add_u32 s40, s38, s40
	s_addc_u32 s41, s39, s41
	s_and_b64 s[42:43], s[44:45], exec
	s_cselect_b32 s15, s41, s47
	s_cselect_b32 s72, s40, s46
	s_ashr_i32 s11, s10, 31
	s_lshl_b64 s[42:43], s[10:11], 19
	v_readlane_b32 s11, v253, 21
	s_add_u32 s42, s11, s42
	v_readlane_b32 s11, v253, 22
	s_addc_u32 s43, s11, s43
	s_and_b64 s[60:61], s[44:45], exec
	s_cselect_b32 s11, s43, s55
	s_cselect_b32 s73, s42, s54
	s_add_u32 s46, s46, 0x40080
	s_addc_u32 s47, s47, 0
	s_add_u32 s74, s54, 0x100
	s_addc_u32 s75, s55, 0
	s_mov_b32 s78, -2
	s_add_u32 s54, s46, 0xfffc0080
	s_addc_u32 s55, s47, -1
	s_add_i32 s76, 16, 0x10000
	s_cmp_eq_u32 s78, 12
	s_cselect_b32 s61, s15, s55
	s_cselect_b32 s60, s72, s54
	v_add_u32_e32 v80, s76, v146
	s_cselect_b32 s55, s11, s75
	s_cselect_b32 s54, s73, s74
	s_add_i32 s77, 16, 0x14000
	ds_read_b128 v[142:145], v80
	ds_read_b128 v[148:151], v80 offset:1024
	ds_read_b128 v[160:163], v80 offset:2048
	ds_read_b128 v[164:167], v80 offset:3072
	v_add_u32_e32 v80, s77, v146
	ds_read_b128 v[168:171], v80
	ds_read_b128 v[172:175], v80 offset:1024
	ds_read_b128 v[176:179], v80 offset:2048
	ds_read_b128 v[180:183], v80 offset:3072
	v_lshl_add_u64 v[208:209], s[46:47], 0, v[138:139]
	s_add_i32 m0, s13, 0xc000
	ds_read_b128 v[184:187], v147
	ds_read_b128 v[188:191], v147 offset:1024
	ds_read_b128 v[204:207], v147 offset:2048
	ds_read_b128 v[214:217], v147 offset:3072
	ds_read_b128 v[218:221], v147 offset:4096
	ds_read_b128 v[222:225], v147 offset:5120
	ds_read_b128 v[226:229], v147 offset:6144
	ds_read_b128 v[230:233], v147 offset:7168
	global_load_lds_dwordx4 v[208:209], off
	v_lshl_add_u64 v[208:209], s[46:47], 0, v[140:141]
	s_add_i32 m0, s13, 0xe000
	s_nop 0
	global_load_lds_dwordx4 v[208:209], off
	s_waitcnt vmcnt(8)
	s_waitcnt lgkmcnt(0)
	s_barrier
	s_waitcnt lgkmcnt(0)
	v_mfma_f32_16x16x32_bf16 v[118:121], v[142:145], v[184:187], 0
	v_mfma_f32_16x16x32_bf16 v[114:117], v[160:163], v[184:187], 0
	v_mfma_f32_16x16x32_bf16 v[106:109], v[142:145], v[204:207], 0
	v_mfma_f32_16x16x32_bf16 v[98:101], v[160:163], v[204:207], 0
	v_mfma_f32_16x16x32_bf16 v[90:93], v[142:145], v[218:221], 0
	v_mfma_f32_16x16x32_bf16 v[82:85], v[160:163], v[218:221], 0
	v_mfma_f32_16x16x32_bf16 v[68:71], v[142:145], v[226:229], 0
	v_mfma_f32_16x16x32_bf16 v[64:67], v[160:163], v[226:229], 0
	v_mfma_f32_16x16x32_bf16 v[118:121], v[148:151], v[188:191], v[118:121]
	v_mfma_f32_16x16x32_bf16 v[114:117], v[164:167], v[188:191], v[114:117]
	v_mfma_f32_16x16x32_bf16 v[106:109], v[148:151], v[214:217], v[106:109]
	v_mfma_f32_16x16x32_bf16 v[98:101], v[164:167], v[214:217], v[98:101]
	v_mfma_f32_16x16x32_bf16 v[90:93], v[148:151], v[222:225], v[90:93]
	v_mfma_f32_16x16x32_bf16 v[82:85], v[164:167], v[222:225], v[82:85]
	v_mfma_f32_16x16x32_bf16 v[68:71], v[148:151], v[230:233], v[68:71]
	v_mfma_f32_16x16x32_bf16 v[64:67], v[164:167], v[230:233], v[64:67]
	v_mfma_f32_16x16x32_bf16 v[126:129], v[168:171], v[184:187], 0
	v_mfma_f32_16x16x32_bf16 v[122:125], v[176:179], v[184:187], 0
	v_mfma_f32_16x16x32_bf16 v[110:113], v[168:171], v[204:207], 0
	v_mfma_f32_16x16x32_bf16 v[102:105], v[176:179], v[204:207], 0
	v_mfma_f32_16x16x32_bf16 v[94:97], v[168:171], v[218:221], 0
	v_mfma_f32_16x16x32_bf16 v[86:89], v[176:179], v[218:221], 0
	v_mfma_f32_16x16x32_bf16 v[76:79], v[168:171], v[226:229], 0
	v_mfma_f32_16x16x32_bf16 v[72:75], v[176:179], v[226:229], 0
	v_mfma_f32_16x16x32_bf16 v[126:129], v[172:175], v[188:191], v[126:129]
	v_mfma_f32_16x16x32_bf16 v[122:125], v[180:183], v[188:191], v[122:125]
	v_mfma_f32_16x16x32_bf16 v[110:113], v[172:175], v[214:217], v[110:113]
	v_mfma_f32_16x16x32_bf16 v[102:105], v[180:183], v[214:217], v[102:105]
	v_mfma_f32_16x16x32_bf16 v[94:97], v[172:175], v[222:225], v[94:97]
	v_mfma_f32_16x16x32_bf16 v[86:89], v[180:183], v[222:225], v[86:89]
	v_mfma_f32_16x16x32_bf16 v[76:79], v[172:175], v[230:233], v[76:79]
	v_mfma_f32_16x16x32_bf16 v[72:75], v[180:183], v[230:233], v[72:75]
	s_barrier
	s_add_i32 s76, s76, s4
	v_lshl_add_u64 v[208:209], s[54:55], 0, v[134:135]
	s_mov_b32 m0, s76
	ds_read_b128 v[184:187], v147 offset:16384
	ds_read_b128 v[188:191], v147 offset:17408
	ds_read_b128 v[204:207], v147 offset:18432
	ds_read_b128 v[214:217], v147 offset:19456
	ds_read_b128 v[218:221], v147 offset:20480
	ds_read_b128 v[222:225], v147 offset:21504
	ds_read_b128 v[226:229], v147 offset:22528
	ds_read_b128 v[230:233], v147 offset:23552
	global_load_lds_dwordx4 v[208:209], off
	s_add_i32 m0, s76, 0x2000
	s_add_u32 s96, s54, 0x40000
	v_lshl_add_u64 v[234:235], s[54:55], 0, v[130:131]
	s_addc_u32 s97, s55, 0
	s_add_i32 s76, s77, s4
	global_load_lds_dwordx4 v[234:235], off
	v_lshl_add_u64 v[236:237], s[96:97], 0, v[134:135]
	s_mov_b32 m0, s76
	v_lshl_add_u64 v[238:239], s[60:61], 0, v[132:133]
	global_load_lds_dwordx4 v[236:237], off
	v_lshl_add_u64 v[236:237], s[96:97], 0, v[130:131]
	s_add_i32 m0, s76, 0x2000
	s_nop 0
	global_load_lds_dwordx4 v[236:237], off
	v_lshl_add_u64 v[236:237], s[60:61], 0, v[136:137]
	s_mov_b32 m0, s13
	s_nop 0
	global_load_lds_dwordx4 v[236:237], off
	s_mov_b32 m0, s25
	s_nop 0
	global_load_lds_dwordx4 v[238:239], off
	s_waitcnt vmcnt(8)
	s_waitcnt lgkmcnt(0)
	s_barrier
	s_waitcnt lgkmcnt(0)
	v_mfma_f32_16x16x32_bf16 v[52:55], v[142:145], v[184:187], 0
	v_mfma_f32_16x16x32_bf16 v[48:51], v[160:163], v[184:187], 0
	v_mfma_f32_16x16x32_bf16 v[36:39], v[142:145], v[204:207], 0
	v_mfma_f32_16x16x32_bf16 v[32:35], v[160:163], v[204:207], 0
	v_mfma_f32_16x16x32_bf16 v[20:23], v[142:145], v[218:221], 0
	v_mfma_f32_16x16x32_bf16 v[16:19], v[160:163], v[218:221], 0
	v_mfma_f32_16x16x32_bf16 v[8:11], v[142:145], v[226:229], 0
	v_mfma_f32_16x16x32_bf16 v[0:3], v[160:163], v[226:229], 0
	v_mfma_f32_16x16x32_bf16 v[52:55], v[148:151], v[188:191], v[52:55]
	v_mfma_f32_16x16x32_bf16 v[48:51], v[164:167], v[188:191], v[48:51]
	v_mfma_f32_16x16x32_bf16 v[36:39], v[148:151], v[214:217], v[36:39]
	v_mfma_f32_16x16x32_bf16 v[32:35], v[164:167], v[214:217], v[32:35]
	v_mfma_f32_16x16x32_bf16 v[20:23], v[148:151], v[222:225], v[20:23]
	v_mfma_f32_16x16x32_bf16 v[16:19], v[164:167], v[222:225], v[16:19]
	v_mfma_f32_16x16x32_bf16 v[8:11], v[148:151], v[230:233], v[8:11]
	v_mfma_f32_16x16x32_bf16 v[0:3], v[164:167], v[230:233], v[0:3]
	v_mfma_f32_16x16x32_bf16 v[60:63], v[168:171], v[184:187], 0
	v_mfma_f32_16x16x32_bf16 v[56:59], v[176:179], v[184:187], 0
	v_mfma_f32_16x16x32_bf16 v[44:47], v[168:171], v[204:207], 0
	v_mfma_f32_16x16x32_bf16 v[40:43], v[176:179], v[204:207], 0
	v_mfma_f32_16x16x32_bf16 v[28:31], v[168:171], v[218:221], 0
	v_mfma_f32_16x16x32_bf16 v[24:27], v[176:179], v[218:221], 0
	v_mfma_f32_16x16x32_bf16 v[12:15], v[168:171], v[226:229], 0
	v_mfma_f32_16x16x32_bf16 v[4:7], v[176:179], v[226:229], 0
	v_mfma_f32_16x16x32_bf16 v[60:63], v[172:175], v[188:191], v[60:63]
	v_mfma_f32_16x16x32_bf16 v[56:59], v[180:183], v[188:191], v[56:59]
	v_mfma_f32_16x16x32_bf16 v[44:47], v[172:175], v[214:217], v[44:47]
	v_mfma_f32_16x16x32_bf16 v[40:43], v[180:183], v[214:217], v[40:43]
	v_mfma_f32_16x16x32_bf16 v[28:31], v[172:175], v[222:225], v[28:31]
	v_mfma_f32_16x16x32_bf16 v[24:27], v[180:183], v[222:225], v[24:27]
	v_mfma_f32_16x16x32_bf16 v[12:15], v[172:175], v[230:233], v[12:15]
	v_mfma_f32_16x16x32_bf16 v[4:7], v[180:183], v[230:233], v[4:7]
	s_barrier
	s_add_i32 s76, 16, 0x18000
	v_add_u32_e32 v80, s76, v146
	s_add_i32 s77, 16, 0x1c000
	ds_read_b128 v[142:145], v80
	ds_read_b128 v[148:151], v80 offset:1024
	ds_read_b128 v[160:163], v80 offset:2048
	ds_read_b128 v[164:167], v80 offset:3072
	v_add_u32_e32 v80, s77, v146
	ds_read_b128 v[168:171], v80
	ds_read_b128 v[172:175], v80 offset:1024
	ds_read_b128 v[176:179], v80 offset:2048
	ds_read_b128 v[180:183], v80 offset:3072
	s_add_u32 s60, s60, 0x40000
	s_addc_u32 s61, s61, 0
	s_mov_b32 m0, s30
	v_lshl_add_u64 v[240:241], s[60:61], 0, v[136:137]
	ds_read_b128 v[184:187], v147 offset:32768
	ds_read_b128 v[188:191], v147 offset:33792
	ds_read_b128 v[204:207], v147 offset:34816
	ds_read_b128 v[214:217], v147 offset:35840
	ds_read_b128 v[218:221], v147 offset:36864
	ds_read_b128 v[222:225], v147 offset:37888
	ds_read_b128 v[226:229], v147 offset:38912
	ds_read_b128 v[230:233], v147 offset:39936
	global_load_lds_dwordx4 v[240:241], off
	v_lshl_add_u64 v[240:241], s[60:61], 0, v[132:133]
	s_mov_b32 m0, s33
	s_nop 0
	global_load_lds_dwordx4 v[240:241], off
	s_waitcnt vmcnt(8)
	s_waitcnt lgkmcnt(0)
	s_barrier
	s_waitcnt lgkmcnt(0)
	v_mfma_f32_16x16x32_bf16 v[118:121], v[142:145], v[184:187], v[118:121]
	v_mfma_f32_16x16x32_bf16 v[114:117], v[160:163], v[184:187], v[114:117]
	v_mfma_f32_16x16x32_bf16 v[106:109], v[142:145], v[204:207], v[106:109]
	v_mfma_f32_16x16x32_bf16 v[98:101], v[160:163], v[204:207], v[98:101]
	v_mfma_f32_16x16x32_bf16 v[90:93], v[142:145], v[218:221], v[90:93]
	v_mfma_f32_16x16x32_bf16 v[82:85], v[160:163], v[218:221], v[82:85]
	v_mfma_f32_16x16x32_bf16 v[68:71], v[142:145], v[226:229], v[68:71]
	v_mfma_f32_16x16x32_bf16 v[64:67], v[160:163], v[226:229], v[64:67]
	v_mfma_f32_16x16x32_bf16 v[118:121], v[148:151], v[188:191], v[118:121]
	v_mfma_f32_16x16x32_bf16 v[114:117], v[164:167], v[188:191], v[114:117]
	v_mfma_f32_16x16x32_bf16 v[106:109], v[148:151], v[214:217], v[106:109]
	v_mfma_f32_16x16x32_bf16 v[98:101], v[164:167], v[214:217], v[98:101]
	v_mfma_f32_16x16x32_bf16 v[90:93], v[148:151], v[222:225], v[90:93]
	v_mfma_f32_16x16x32_bf16 v[82:85], v[164:167], v[222:225], v[82:85]
	v_mfma_f32_16x16x32_bf16 v[68:71], v[148:151], v[230:233], v[68:71]
	v_mfma_f32_16x16x32_bf16 v[64:67], v[164:167], v[230:233], v[64:67]
	v_mfma_f32_16x16x32_bf16 v[126:129], v[168:171], v[184:187], v[126:129]
	v_mfma_f32_16x16x32_bf16 v[122:125], v[176:179], v[184:187], v[122:125]
	v_mfma_f32_16x16x32_bf16 v[110:113], v[168:171], v[204:207], v[110:113]
	v_mfma_f32_16x16x32_bf16 v[102:105], v[176:179], v[204:207], v[102:105]
	v_mfma_f32_16x16x32_bf16 v[94:97], v[168:171], v[218:221], v[94:97]
	v_mfma_f32_16x16x32_bf16 v[86:89], v[176:179], v[218:221], v[86:89]
	v_mfma_f32_16x16x32_bf16 v[76:79], v[168:171], v[226:229], v[76:79]
	v_mfma_f32_16x16x32_bf16 v[72:75], v[176:179], v[226:229], v[72:75]
	v_mfma_f32_16x16x32_bf16 v[126:129], v[172:175], v[188:191], v[126:129]
	v_mfma_f32_16x16x32_bf16 v[122:125], v[180:183], v[188:191], v[122:125]
	v_mfma_f32_16x16x32_bf16 v[110:113], v[172:175], v[214:217], v[110:113]
	v_mfma_f32_16x16x32_bf16 v[102:105], v[180:183], v[214:217], v[102:105]
	v_mfma_f32_16x16x32_bf16 v[94:97], v[172:175], v[222:225], v[94:97]
	v_mfma_f32_16x16x32_bf16 v[86:89], v[180:183], v[222:225], v[86:89]
	v_mfma_f32_16x16x32_bf16 v[76:79], v[172:175], v[230:233], v[76:79]
	v_mfma_f32_16x16x32_bf16 v[72:75], v[180:183], v[230:233], v[72:75]
	s_barrier
	s_add_i32 s60, s76, s4
	v_lshl_add_u64 v[208:209], v[208:209], 0, s[20:21]
	s_mov_b32 m0, s60
	ds_read_b128 v[184:187], v147 offset:49152
	ds_read_b128 v[188:191], v147 offset:50176
	ds_read_b128 v[204:207], v147 offset:51200
	ds_read_b128 v[214:217], v147 offset:52224
	ds_read_b128 v[218:221], v147 offset:53248
	ds_read_b128 v[222:225], v147 offset:54272
	ds_read_b128 v[226:229], v147 offset:55296
	ds_read_b128 v[230:233], v147 offset:56320
	global_load_lds_dwordx4 v[208:209], off
	s_add_i32 m0, s60, 0x2000
	s_add_u32 s54, s54, 0x40080
	v_lshl_add_u64 v[208:209], v[234:235], 0, s[20:21]
	s_addc_u32 s55, s55, 0
	s_add_i32 s60, s77, s4
	global_load_lds_dwordx4 v[208:209], off
	v_lshl_add_u64 v[208:209], s[54:55], 0, v[134:135]
	s_mov_b32 m0, s60
	s_nop 0
	global_load_lds_dwordx4 v[208:209], off
	v_lshl_add_u64 v[208:209], s[54:55], 0, v[130:131]
	s_add_i32 m0, s60, 0x2000
	s_nop 0
	global_load_lds_dwordx4 v[208:209], off
	v_lshl_add_u64 v[208:209], v[236:237], 0, s[20:21]
	s_mov_b32 m0, s34
	s_nop 0
	global_load_lds_dwordx4 v[208:209], off
	v_lshl_add_u64 v[208:209], v[238:239], 0, s[20:21]
	s_mov_b32 m0, s36
	s_nop 0
	global_load_lds_dwordx4 v[208:209], off
	s_waitcnt vmcnt(8)
	s_waitcnt lgkmcnt(0)
	s_barrier
	s_waitcnt lgkmcnt(0)
	v_mfma_f32_16x16x32_bf16 v[52:55], v[142:145], v[184:187], v[52:55]
	v_mfma_f32_16x16x32_bf16 v[48:51], v[160:163], v[184:187], v[48:51]
	v_mfma_f32_16x16x32_bf16 v[36:39], v[142:145], v[204:207], v[36:39]
	v_mfma_f32_16x16x32_bf16 v[32:35], v[160:163], v[204:207], v[32:35]
	v_mfma_f32_16x16x32_bf16 v[20:23], v[142:145], v[218:221], v[20:23]
	v_mfma_f32_16x16x32_bf16 v[16:19], v[160:163], v[218:221], v[16:19]
	v_mfma_f32_16x16x32_bf16 v[8:11], v[142:145], v[226:229], v[8:11]
	v_mfma_f32_16x16x32_bf16 v[0:3], v[160:163], v[226:229], v[0:3]
	v_mfma_f32_16x16x32_bf16 v[52:55], v[148:151], v[188:191], v[52:55]
	v_mfma_f32_16x16x32_bf16 v[48:51], v[164:167], v[188:191], v[48:51]
	v_mfma_f32_16x16x32_bf16 v[36:39], v[148:151], v[214:217], v[36:39]
	v_mfma_f32_16x16x32_bf16 v[32:35], v[164:167], v[214:217], v[32:35]
	v_mfma_f32_16x16x32_bf16 v[20:23], v[148:151], v[222:225], v[20:23]
	v_mfma_f32_16x16x32_bf16 v[16:19], v[164:167], v[222:225], v[16:19]
	v_mfma_f32_16x16x32_bf16 v[8:11], v[148:151], v[230:233], v[8:11]
	v_mfma_f32_16x16x32_bf16 v[0:3], v[164:167], v[230:233], v[0:3]
	v_mfma_f32_16x16x32_bf16 v[60:63], v[168:171], v[184:187], v[60:63]
	v_mfma_f32_16x16x32_bf16 v[56:59], v[176:179], v[184:187], v[56:59]
	v_mfma_f32_16x16x32_bf16 v[44:47], v[168:171], v[204:207], v[44:47]
	v_mfma_f32_16x16x32_bf16 v[40:43], v[176:179], v[204:207], v[40:43]
	v_mfma_f32_16x16x32_bf16 v[28:31], v[168:171], v[218:221], v[28:31]
	v_mfma_f32_16x16x32_bf16 v[24:27], v[176:179], v[218:221], v[24:27]
	v_mfma_f32_16x16x32_bf16 v[12:15], v[168:171], v[226:229], v[12:15]
	v_mfma_f32_16x16x32_bf16 v[4:7], v[176:179], v[226:229], v[4:7]
	v_mfma_f32_16x16x32_bf16 v[60:63], v[172:175], v[188:191], v[60:63]
	v_mfma_f32_16x16x32_bf16 v[56:59], v[180:183], v[188:191], v[56:59]
	v_mfma_f32_16x16x32_bf16 v[44:47], v[172:175], v[214:217], v[44:47]
	v_mfma_f32_16x16x32_bf16 v[40:43], v[180:183], v[214:217], v[40:43]
	v_mfma_f32_16x16x32_bf16 v[28:31], v[172:175], v[222:225], v[28:31]
	v_mfma_f32_16x16x32_bf16 v[24:27], v[180:183], v[222:225], v[24:27]
	v_mfma_f32_16x16x32_bf16 v[12:15], v[172:175], v[230:233], v[12:15]
	v_mfma_f32_16x16x32_bf16 v[4:7], v[180:183], v[230:233], v[4:7]
	s_barrier
	s_add_i32 s78, s78, 2
	s_add_u32 s46, s46, 0x100
	s_addc_u32 s47, s47, 0
	s_add_u32 s74, s74, 0x100
	s_addc_u32 s75, s75, 0
	s_cmp_gt_u32 s78, 13

.LBB0_250:
	s_ashr_i32 s15, s14, 31
	s_lshl_b64 s[40:41], s[14:15], 18
	s_add_u32 s40, s94, s40
	s_addc_u32 s41, s95, s41
	s_and_b64 s[42:43], s[44:45], exec
	s_cselect_b32 s15, s41, s47
	s_cselect_b32 s60, s40, s46
	s_ashr_i32 s11, s10, 31
	s_lshl_b64 s[42:43], s[10:11], 18
	v_readlane_b32 s54, v254, 21
	v_readlane_b32 s55, v254, 22
	s_add_u32 s42, s54, s42
	s_addc_u32 s43, s55, s43
	s_and_b64 s[54:55], s[44:45], exec
	s_cselect_b32 s11, s43, s51
	s_cselect_b32 s61, s42, s50
	s_add_u32 s46, s46, 0x20080
	s_addc_u32 s47, s47, 0
	s_add_u32 s66, s50, 0x100
	s_addc_u32 s67, s51, 0
	s_mov_b32 s72, -2
	s_add_u32 s50, s46, 0xfffe0080
	s_addc_u32 s51, s47, -1
	s_add_i32 s73, 16, 0x10000
	s_cmp_eq_u32 s72, 4
	s_cselect_b32 s55, s15, s51
	s_cselect_b32 s54, s60, s50
	v_add_u32_e32 v146, s73, v80
	s_cselect_b32 s51, s11, s67
	s_cselect_b32 s50, s61, s66
	s_add_i32 s76, 16, 0x14000
	ds_read_b128 v[142:145], v146
	ds_read_b128 v[160:163], v146 offset:1024
	ds_read_b128 v[164:167], v146 offset:2048
	ds_read_b128 v[168:171], v146 offset:3072
	v_add_u32_e32 v146, s76, v80
	ds_read_b128 v[172:175], v146
	ds_read_b128 v[176:179], v146 offset:1024
	ds_read_b128 v[180:183], v146 offset:2048
	ds_read_b128 v[184:187], v146 offset:3072
	v_lshl_add_u64 v[146:147], s[46:47], 0, v[138:139]
	s_add_i32 m0, s13, 0xc000
	ds_read_b128 v[188:191], v148
	ds_read_b128 v[204:207], v148 offset:1024
	ds_read_b128 v[214:217], v148 offset:2048
	ds_read_b128 v[218:221], v148 offset:3072
	ds_read_b128 v[222:225], v148 offset:4096
	ds_read_b128 v[226:229], v148 offset:5120
	ds_read_b128 v[230:233], v148 offset:6144
	ds_read_b128 v[234:237], v148 offset:7168
	global_load_lds_dwordx4 v[146:147], off
	v_lshl_add_u64 v[146:147], s[46:47], 0, v[140:141]
	s_add_i32 m0, s13, 0xe000
	s_nop 0
	global_load_lds_dwordx4 v[146:147], off
	s_waitcnt vmcnt(8)
	s_waitcnt lgkmcnt(0)
	s_barrier
	s_waitcnt lgkmcnt(0)
	v_mfma_f32_16x16x32_bf16 v[126:129], v[142:145], v[188:191], 0
	v_mfma_f32_16x16x32_bf16 v[122:125], v[164:167], v[188:191], 0
	v_mfma_f32_16x16x32_bf16 v[110:113], v[142:145], v[214:217], 0
	v_mfma_f32_16x16x32_bf16 v[106:109], v[164:167], v[214:217], 0
	v_mfma_f32_16x16x32_bf16 v[94:97], v[142:145], v[222:225], 0
	v_mfma_f32_16x16x32_bf16 v[90:93], v[164:167], v[222:225], 0
	v_mfma_f32_16x16x32_bf16 v[76:79], v[142:145], v[230:233], 0
	v_mfma_f32_16x16x32_bf16 v[72:75], v[164:167], v[230:233], 0
	v_mfma_f32_16x16x32_bf16 v[126:129], v[160:163], v[204:207], v[126:129]
	v_mfma_f32_16x16x32_bf16 v[122:125], v[168:171], v[204:207], v[122:125]
	v_mfma_f32_16x16x32_bf16 v[110:113], v[160:163], v[218:221], v[110:113]
	v_mfma_f32_16x16x32_bf16 v[106:109], v[168:171], v[218:221], v[106:109]
	v_mfma_f32_16x16x32_bf16 v[94:97], v[160:163], v[226:229], v[94:97]
	v_mfma_f32_16x16x32_bf16 v[90:93], v[168:171], v[226:229], v[90:93]
	v_mfma_f32_16x16x32_bf16 v[76:79], v[160:163], v[234:237], v[76:79]
	v_mfma_f32_16x16x32_bf16 v[72:75], v[168:171], v[234:237], v[72:75]
	v_mfma_f32_16x16x32_bf16 v[118:121], v[172:175], v[188:191], 0
	v_mfma_f32_16x16x32_bf16 v[114:117], v[180:183], v[188:191], 0
	v_mfma_f32_16x16x32_bf16 v[102:105], v[172:175], v[214:217], 0
	v_mfma_f32_16x16x32_bf16 v[98:101], v[180:183], v[214:217], 0
	v_mfma_f32_16x16x32_bf16 v[86:89], v[172:175], v[222:225], 0
	v_mfma_f32_16x16x32_bf16 v[82:85], v[180:183], v[222:225], 0
	v_mfma_f32_16x16x32_bf16 v[68:71], v[172:175], v[230:233], 0
	v_mfma_f32_16x16x32_bf16 v[64:67], v[180:183], v[230:233], 0
	v_mfma_f32_16x16x32_bf16 v[118:121], v[176:179], v[204:207], v[118:121]
	v_mfma_f32_16x16x32_bf16 v[114:117], v[184:187], v[204:207], v[114:117]
	v_mfma_f32_16x16x32_bf16 v[102:105], v[176:179], v[218:221], v[102:105]
	v_mfma_f32_16x16x32_bf16 v[98:101], v[184:187], v[218:221], v[98:101]
	v_mfma_f32_16x16x32_bf16 v[86:89], v[176:179], v[226:229], v[86:89]
	v_mfma_f32_16x16x32_bf16 v[82:85], v[184:187], v[226:229], v[82:85]
	v_mfma_f32_16x16x32_bf16 v[68:71], v[176:179], v[234:237], v[68:71]
	v_mfma_f32_16x16x32_bf16 v[64:67], v[184:187], v[234:237], v[64:67]
	s_barrier
	s_add_i32 s73, s73, s4
	v_lshl_add_u64 v[146:147], s[50:51], 0, v[134:135]
	s_mov_b32 m0, s73
	ds_read_b128 v[188:191], v148 offset:16384
	ds_read_b128 v[204:207], v148 offset:17408
	ds_read_b128 v[214:217], v148 offset:18432
	ds_read_b128 v[218:221], v148 offset:19456
	ds_read_b128 v[222:225], v148 offset:20480
	ds_read_b128 v[226:229], v148 offset:21504
	ds_read_b128 v[230:233], v148 offset:22528
	ds_read_b128 v[234:237], v148 offset:23552
	global_load_lds_dwordx4 v[146:147], off
	s_add_i32 m0, s73, 0x2000
	s_add_u32 s74, s50, 0x20000
	v_lshl_add_u64 v[150:151], s[50:51], 0, v[130:131]
	s_addc_u32 s75, s51, 0
	s_add_i32 s73, s76, s4
	global_load_lds_dwordx4 v[150:151], off
	v_lshl_add_u64 v[208:209], s[74:75], 0, v[134:135]
	s_mov_b32 m0, s73
	v_lshl_add_u64 v[238:239], s[54:55], 0, v[132:133]
	global_load_lds_dwordx4 v[208:209], off
	v_lshl_add_u64 v[208:209], s[74:75], 0, v[130:131]
	s_add_i32 m0, s73, 0x2000
	s_nop 0
	global_load_lds_dwordx4 v[208:209], off
	v_lshl_add_u64 v[208:209], s[54:55], 0, v[136:137]
	s_mov_b32 m0, s13
	s_nop 0
	global_load_lds_dwordx4 v[208:209], off
	s_mov_b32 m0, s25
	s_nop 0
	global_load_lds_dwordx4 v[238:239], off
	s_waitcnt vmcnt(8)
	s_waitcnt lgkmcnt(0)
	s_barrier
	s_waitcnt lgkmcnt(0)
	v_mfma_f32_16x16x32_bf16 v[60:63], v[142:145], v[188:191], 0
	v_mfma_f32_16x16x32_bf16 v[56:59], v[164:167], v[188:191], 0
	v_mfma_f32_16x16x32_bf16 v[44:47], v[142:145], v[214:217], 0
	v_mfma_f32_16x16x32_bf16 v[40:43], v[164:167], v[214:217], 0
	v_mfma_f32_16x16x32_bf16 v[28:31], v[142:145], v[222:225], 0
	v_mfma_f32_16x16x32_bf16 v[24:27], v[164:167], v[222:225], 0
	v_mfma_f32_16x16x32_bf16 v[12:15], v[142:145], v[230:233], 0
	v_mfma_f32_16x16x32_bf16 v[8:11], v[164:167], v[230:233], 0
	v_mfma_f32_16x16x32_bf16 v[60:63], v[160:163], v[204:207], v[60:63]
	v_mfma_f32_16x16x32_bf16 v[56:59], v[168:171], v[204:207], v[56:59]
	v_mfma_f32_16x16x32_bf16 v[44:47], v[160:163], v[218:221], v[44:47]
	v_mfma_f32_16x16x32_bf16 v[40:43], v[168:171], v[218:221], v[40:43]
	v_mfma_f32_16x16x32_bf16 v[28:31], v[160:163], v[226:229], v[28:31]
	v_mfma_f32_16x16x32_bf16 v[24:27], v[168:171], v[226:229], v[24:27]
	v_mfma_f32_16x16x32_bf16 v[12:15], v[160:163], v[234:237], v[12:15]
	v_mfma_f32_16x16x32_bf16 v[8:11], v[168:171], v[234:237], v[8:11]
	v_mfma_f32_16x16x32_bf16 v[52:55], v[172:175], v[188:191], 0
	v_mfma_f32_16x16x32_bf16 v[48:51], v[180:183], v[188:191], 0
	v_mfma_f32_16x16x32_bf16 v[36:39], v[172:175], v[214:217], 0
	v_mfma_f32_16x16x32_bf16 v[32:35], v[180:183], v[214:217], 0
	v_mfma_f32_16x16x32_bf16 v[20:23], v[172:175], v[222:225], 0
	v_mfma_f32_16x16x32_bf16 v[16:19], v[180:183], v[222:225], 0
	v_mfma_f32_16x16x32_bf16 v[4:7], v[172:175], v[230:233], 0
	v_mfma_f32_16x16x32_bf16 v[0:3], v[180:183], v[230:233], 0
	v_mfma_f32_16x16x32_bf16 v[52:55], v[176:179], v[204:207], v[52:55]
	v_mfma_f32_16x16x32_bf16 v[48:51], v[184:187], v[204:207], v[48:51]
	v_mfma_f32_16x16x32_bf16 v[36:39], v[176:179], v[218:221], v[36:39]
	v_mfma_f32_16x16x32_bf16 v[32:35], v[184:187], v[218:221], v[32:35]
	v_mfma_f32_16x16x32_bf16 v[20:23], v[176:179], v[226:229], v[20:23]
	v_mfma_f32_16x16x32_bf16 v[16:19], v[184:187], v[226:229], v[16:19]
	v_mfma_f32_16x16x32_bf16 v[4:7], v[176:179], v[234:237], v[4:7]
	v_mfma_f32_16x16x32_bf16 v[0:3], v[184:187], v[234:237], v[0:3]
	s_barrier
	s_add_i32 s73, 16, 0x18000
	v_add_u32_e32 v149, s73, v80
	s_add_i32 s74, 16, 0x1c000
	ds_read_b128 v[142:145], v149
	ds_read_b128 v[160:163], v149 offset:1024
	ds_read_b128 v[164:167], v149 offset:2048
	ds_read_b128 v[168:171], v149 offset:3072
	v_add_u32_e32 v149, s74, v80
	ds_read_b128 v[172:175], v149
	ds_read_b128 v[176:179], v149 offset:1024
	ds_read_b128 v[180:183], v149 offset:2048
	ds_read_b128 v[184:187], v149 offset:3072
	s_add_u32 s54, s54, 0x20000
	s_addc_u32 s55, s55, 0
	s_mov_b32 m0, s30
	v_lshl_add_u64 v[240:241], s[54:55], 0, v[136:137]
	ds_read_b128 v[188:191], v148 offset:32768
	ds_read_b128 v[204:207], v148 offset:33792
	ds_read_b128 v[214:217], v148 offset:34816
	ds_read_b128 v[218:221], v148 offset:35840
	ds_read_b128 v[222:225], v148 offset:36864
	ds_read_b128 v[226:229], v148 offset:37888
	ds_read_b128 v[230:233], v148 offset:38912
	ds_read_b128 v[234:237], v148 offset:39936
	global_load_lds_dwordx4 v[240:241], off
	v_lshl_add_u64 v[240:241], s[54:55], 0, v[132:133]
	s_mov_b32 m0, s33
	s_nop 0
	global_load_lds_dwordx4 v[240:241], off
	s_waitcnt vmcnt(8)
	s_waitcnt lgkmcnt(0)
	s_barrier
	s_waitcnt lgkmcnt(0)
	v_mfma_f32_16x16x32_bf16 v[126:129], v[142:145], v[188:191], v[126:129]
	v_mfma_f32_16x16x32_bf16 v[122:125], v[164:167], v[188:191], v[122:125]
	v_mfma_f32_16x16x32_bf16 v[110:113], v[142:145], v[214:217], v[110:113]
	v_mfma_f32_16x16x32_bf16 v[106:109], v[164:167], v[214:217], v[106:109]
	v_mfma_f32_16x16x32_bf16 v[94:97], v[142:145], v[222:225], v[94:97]
	v_mfma_f32_16x16x32_bf16 v[90:93], v[164:167], v[222:225], v[90:93]
	v_mfma_f32_16x16x32_bf16 v[76:79], v[142:145], v[230:233], v[76:79]
	v_mfma_f32_16x16x32_bf16 v[72:75], v[164:167], v[230:233], v[72:75]
	v_mfma_f32_16x16x32_bf16 v[126:129], v[160:163], v[204:207], v[126:129]
	v_mfma_f32_16x16x32_bf16 v[122:125], v[168:171], v[204:207], v[122:125]
	v_mfma_f32_16x16x32_bf16 v[110:113], v[160:163], v[218:221], v[110:113]
	v_mfma_f32_16x16x32_bf16 v[106:109], v[168:171], v[218:221], v[106:109]
	v_mfma_f32_16x16x32_bf16 v[94:97], v[160:163], v[226:229], v[94:97]
	v_mfma_f32_16x16x32_bf16 v[90:93], v[168:171], v[226:229], v[90:93]
	v_mfma_f32_16x16x32_bf16 v[76:79], v[160:163], v[234:237], v[76:79]
	v_mfma_f32_16x16x32_bf16 v[72:75], v[168:171], v[234:237], v[72:75]
	v_mfma_f32_16x16x32_bf16 v[118:121], v[172:175], v[188:191], v[118:121]
	v_mfma_f32_16x16x32_bf16 v[114:117], v[180:183], v[188:191], v[114:117]
	v_mfma_f32_16x16x32_bf16 v[102:105], v[172:175], v[214:217], v[102:105]
	v_mfma_f32_16x16x32_bf16 v[98:101], v[180:183], v[214:217], v[98:101]
	v_mfma_f32_16x16x32_bf16 v[86:89], v[172:175], v[222:225], v[86:89]
	v_mfma_f32_16x16x32_bf16 v[82:85], v[180:183], v[222:225], v[82:85]
	v_mfma_f32_16x16x32_bf16 v[68:71], v[172:175], v[230:233], v[68:71]
	v_mfma_f32_16x16x32_bf16 v[64:67], v[180:183], v[230:233], v[64:67]
	v_mfma_f32_16x16x32_bf16 v[118:121], v[176:179], v[204:207], v[118:121]
	v_mfma_f32_16x16x32_bf16 v[114:117], v[184:187], v[204:207], v[114:117]
	v_mfma_f32_16x16x32_bf16 v[102:105], v[176:179], v[218:221], v[102:105]
	v_mfma_f32_16x16x32_bf16 v[98:101], v[184:187], v[218:221], v[98:101]
	v_mfma_f32_16x16x32_bf16 v[86:89], v[176:179], v[226:229], v[86:89]
	v_mfma_f32_16x16x32_bf16 v[82:85], v[184:187], v[226:229], v[82:85]
	v_mfma_f32_16x16x32_bf16 v[68:71], v[176:179], v[234:237], v[68:71]
	v_mfma_f32_16x16x32_bf16 v[64:67], v[184:187], v[234:237], v[64:67]
	s_barrier
	s_add_i32 s54, s73, s4
	v_lshl_add_u64 v[146:147], v[146:147], 0, s[20:21]
	s_mov_b32 m0, s54
	ds_read_b128 v[188:191], v148 offset:49152
	ds_read_b128 v[204:207], v148 offset:50176
	ds_read_b128 v[214:217], v148 offset:51200
	ds_read_b128 v[218:221], v148 offset:52224
	ds_read_b128 v[222:225], v148 offset:53248
	ds_read_b128 v[226:229], v148 offset:54272
	ds_read_b128 v[230:233], v148 offset:55296
	ds_read_b128 v[234:237], v148 offset:56320
	global_load_lds_dwordx4 v[146:147], off
	s_add_i32 m0, s54, 0x2000
	s_add_u32 s50, s50, 0x20080
	v_lshl_add_u64 v[146:147], v[150:151], 0, s[20:21]
	s_addc_u32 s51, s51, 0
	s_add_i32 s54, s74, s4
	global_load_lds_dwordx4 v[146:147], off
	v_lshl_add_u64 v[146:147], s[50:51], 0, v[134:135]
	s_mov_b32 m0, s54
	s_nop 0
	global_load_lds_dwordx4 v[146:147], off
	v_lshl_add_u64 v[146:147], s[50:51], 0, v[130:131]
	s_add_i32 m0, s54, 0x2000
	s_nop 0
	global_load_lds_dwordx4 v[146:147], off
	v_lshl_add_u64 v[146:147], v[208:209], 0, s[20:21]
	s_mov_b32 m0, s34
	s_nop 0
	global_load_lds_dwordx4 v[146:147], off
	v_lshl_add_u64 v[146:147], v[238:239], 0, s[20:21]
	s_mov_b32 m0, s36
	s_nop 0
	global_load_lds_dwordx4 v[146:147], off
	s_waitcnt vmcnt(8)
	s_waitcnt lgkmcnt(0)
	s_barrier
	s_waitcnt lgkmcnt(0)
	v_mfma_f32_16x16x32_bf16 v[60:63], v[142:145], v[188:191], v[60:63]
	v_mfma_f32_16x16x32_bf16 v[56:59], v[164:167], v[188:191], v[56:59]
	v_mfma_f32_16x16x32_bf16 v[44:47], v[142:145], v[214:217], v[44:47]
	v_mfma_f32_16x16x32_bf16 v[40:43], v[164:167], v[214:217], v[40:43]
	v_mfma_f32_16x16x32_bf16 v[28:31], v[142:145], v[222:225], v[28:31]
	v_mfma_f32_16x16x32_bf16 v[24:27], v[164:167], v[222:225], v[24:27]
	v_mfma_f32_16x16x32_bf16 v[12:15], v[142:145], v[230:233], v[12:15]
	v_mfma_f32_16x16x32_bf16 v[8:11], v[164:167], v[230:233], v[8:11]
	v_mfma_f32_16x16x32_bf16 v[60:63], v[160:163], v[204:207], v[60:63]
	v_mfma_f32_16x16x32_bf16 v[56:59], v[168:171], v[204:207], v[56:59]
	v_mfma_f32_16x16x32_bf16 v[44:47], v[160:163], v[218:221], v[44:47]
	v_mfma_f32_16x16x32_bf16 v[40:43], v[168:171], v[218:221], v[40:43]
	v_mfma_f32_16x16x32_bf16 v[28:31], v[160:163], v[226:229], v[28:31]
	v_mfma_f32_16x16x32_bf16 v[24:27], v[168:171], v[226:229], v[24:27]
	v_mfma_f32_16x16x32_bf16 v[12:15], v[160:163], v[234:237], v[12:15]
	v_mfma_f32_16x16x32_bf16 v[8:11], v[168:171], v[234:237], v[8:11]
	v_mfma_f32_16x16x32_bf16 v[52:55], v[172:175], v[188:191], v[52:55]
	v_mfma_f32_16x16x32_bf16 v[48:51], v[180:183], v[188:191], v[48:51]
	v_mfma_f32_16x16x32_bf16 v[36:39], v[172:175], v[214:217], v[36:39]
	v_mfma_f32_16x16x32_bf16 v[32:35], v[180:183], v[214:217], v[32:35]
	v_mfma_f32_16x16x32_bf16 v[20:23], v[172:175], v[222:225], v[20:23]
	v_mfma_f32_16x16x32_bf16 v[16:19], v[180:183], v[222:225], v[16:19]
	v_mfma_f32_16x16x32_bf16 v[4:7], v[172:175], v[230:233], v[4:7]
	v_mfma_f32_16x16x32_bf16 v[0:3], v[180:183], v[230:233], v[0:3]
	v_mfma_f32_16x16x32_bf16 v[52:55], v[176:179], v[204:207], v[52:55]
	v_mfma_f32_16x16x32_bf16 v[48:51], v[184:187], v[204:207], v[48:51]
	v_mfma_f32_16x16x32_bf16 v[36:39], v[176:179], v[218:221], v[36:39]
	v_mfma_f32_16x16x32_bf16 v[32:35], v[184:187], v[218:221], v[32:35]
	v_mfma_f32_16x16x32_bf16 v[20:23], v[176:179], v[226:229], v[20:23]
	v_mfma_f32_16x16x32_bf16 v[16:19], v[184:187], v[226:229], v[16:19]
	v_mfma_f32_16x16x32_bf16 v[4:7], v[176:179], v[234:237], v[4:7]
	v_mfma_f32_16x16x32_bf16 v[0:3], v[184:187], v[234:237], v[0:3]
	s_barrier
	s_add_i32 s72, s72, 2
	s_add_u32 s46, s46, 0x100
	s_addc_u32 s47, s47, 0
	s_add_u32 s66, s66, 0x100
	s_addc_u32 s67, s67, 0
	s_cmp_gt_u32 s72, 5

.LBB0_291:
	s_ashr_i32 s11, s10, 31
	s_lshl_b64 s[0:1], s[10:11], 19
	s_add_u32 s74, s38, s0
	s_addc_u32 s75, s39, s1
	s_and_b64 s[0:1], s[44:45], exec
	s_cselect_b32 s11, s75, s47
	s_cselect_b32 s53, s74, s46
	s_ashr_i32 s43, s42, 31
	s_lshl_b64 s[0:1], s[42:43], 19
	v_readlane_b32 s50, v254, 2
	v_readlane_b32 s51, v254, 3
	s_add_u32 s0, s50, s0
	s_addc_u32 s1, s51, s1
	s_and_b64 s[50:51], s[44:45], exec
	s_cselect_b32 s43, s1, s49
	s_cselect_b32 s54, s0, s48
	s_add_u32 s46, s46, 0x40080
	s_addc_u32 s47, s47, 0
	s_add_u32 s55, s48, 0x100
	s_addc_u32 s56, s49, 0
	s_mov_b32 s57, -2
	s_add_u32 s48, s46, 0xfffc0080
	s_addc_u32 s49, s47, -1
	s_add_i32 s60, 16, 0x10000
	s_cmp_eq_u32 s57, 12
	s_cselect_b32 s51, s11, s49
	s_cselect_b32 s50, s53, s48
	v_add_u32_e32 v80, s60, v186
	s_cselect_b32 s49, s43, s56
	s_cselect_b32 s48, s54, s55
	s_add_i32 s67, 16, 0x14000
	ds_read_b128 v[130:133], v80
	ds_read_b128 v[134:137], v80 offset:1024
	ds_read_b128 v[138:141], v80 offset:2048
	ds_read_b128 v[162:165], v80 offset:3072
	v_add_u32_e32 v80, s67, v186
	ds_read_b128 v[166:169], v80
	ds_read_b128 v[170:173], v80 offset:1024
	ds_read_b128 v[174:177], v80 offset:2048
	ds_read_b128 v[178:181], v80 offset:3072
	v_lshl_add_u64 v[208:209], s[46:47], 0, v[150:151]
	s_add_i32 m0, s25, 0xc000
	ds_read_b128 v[182:185], v187
	ds_read_b128 v[188:191], v187 offset:1024
	ds_read_b128 v[204:207], v187 offset:2048
	ds_read_b128 v[214:217], v187 offset:3072
	ds_read_b128 v[218:221], v187 offset:4096
	ds_read_b128 v[222:225], v187 offset:5120
	ds_read_b128 v[226:229], v187 offset:6144
	ds_read_b128 v[230:233], v187 offset:7168
	global_load_lds_dwordx4 v[208:209], off
	v_lshl_add_u64 v[208:209], s[46:47], 0, v[160:161]
	s_add_i32 m0, s25, 0xe000
	s_nop 0
	global_load_lds_dwordx4 v[208:209], off
	s_waitcnt vmcnt(8)
	s_waitcnt lgkmcnt(0)
	s_barrier
	s_waitcnt lgkmcnt(0)
	v_mfma_f32_16x16x32_bf16 v[126:129], v[130:133], v[182:185], 0
	v_mfma_f32_16x16x32_bf16 v[122:125], v[138:141], v[182:185], 0
	v_mfma_f32_16x16x32_bf16 v[110:113], v[130:133], v[204:207], 0
	v_mfma_f32_16x16x32_bf16 v[106:109], v[138:141], v[204:207], 0
	v_mfma_f32_16x16x32_bf16 v[94:97], v[130:133], v[218:221], 0
	v_mfma_f32_16x16x32_bf16 v[90:93], v[138:141], v[218:221], 0
	v_mfma_f32_16x16x32_bf16 v[76:79], v[130:133], v[226:229], 0
	v_mfma_f32_16x16x32_bf16 v[72:75], v[138:141], v[226:229], 0
	v_mfma_f32_16x16x32_bf16 v[126:129], v[134:137], v[188:191], v[126:129]
	v_mfma_f32_16x16x32_bf16 v[122:125], v[162:165], v[188:191], v[122:125]
	v_mfma_f32_16x16x32_bf16 v[110:113], v[134:137], v[214:217], v[110:113]
	v_mfma_f32_16x16x32_bf16 v[106:109], v[162:165], v[214:217], v[106:109]
	v_mfma_f32_16x16x32_bf16 v[94:97], v[134:137], v[222:225], v[94:97]
	v_mfma_f32_16x16x32_bf16 v[90:93], v[162:165], v[222:225], v[90:93]
	v_mfma_f32_16x16x32_bf16 v[76:79], v[134:137], v[230:233], v[76:79]
	v_mfma_f32_16x16x32_bf16 v[72:75], v[162:165], v[230:233], v[72:75]
	v_mfma_f32_16x16x32_bf16 v[118:121], v[166:169], v[182:185], 0
	v_mfma_f32_16x16x32_bf16 v[114:117], v[174:177], v[182:185], 0
	v_mfma_f32_16x16x32_bf16 v[102:105], v[166:169], v[204:207], 0
	v_mfma_f32_16x16x32_bf16 v[98:101], v[174:177], v[204:207], 0
	v_mfma_f32_16x16x32_bf16 v[86:89], v[166:169], v[218:221], 0
	v_mfma_f32_16x16x32_bf16 v[82:85], v[174:177], v[218:221], 0
	v_mfma_f32_16x16x32_bf16 v[68:71], v[166:169], v[226:229], 0
	v_mfma_f32_16x16x32_bf16 v[64:67], v[174:177], v[226:229], 0
	v_mfma_f32_16x16x32_bf16 v[118:121], v[170:173], v[188:191], v[118:121]
	v_mfma_f32_16x16x32_bf16 v[114:117], v[178:181], v[188:191], v[114:117]
	v_mfma_f32_16x16x32_bf16 v[102:105], v[170:173], v[214:217], v[102:105]
	v_mfma_f32_16x16x32_bf16 v[98:101], v[178:181], v[214:217], v[98:101]
	v_mfma_f32_16x16x32_bf16 v[86:89], v[170:173], v[222:225], v[86:89]
	v_mfma_f32_16x16x32_bf16 v[82:85], v[178:181], v[222:225], v[82:85]
	v_mfma_f32_16x16x32_bf16 v[68:71], v[170:173], v[230:233], v[68:71]
	v_mfma_f32_16x16x32_bf16 v[64:67], v[178:181], v[230:233], v[64:67]
	s_barrier
	s_add_i32 s60, s60, s13
	v_lshl_add_u64 v[208:209], s[48:49], 0, v[146:147]
	s_mov_b32 m0, s60
	ds_read_b128 v[182:185], v187 offset:16384
	ds_read_b128 v[188:191], v187 offset:17408
	ds_read_b128 v[204:207], v187 offset:18432
	ds_read_b128 v[214:217], v187 offset:19456
	ds_read_b128 v[218:221], v187 offset:20480
	ds_read_b128 v[222:225], v187 offset:21504
	ds_read_b128 v[226:229], v187 offset:22528
	ds_read_b128 v[230:233], v187 offset:23552
	global_load_lds_dwordx4 v[208:209], off
	s_add_i32 m0, s60, 0x2000
	s_add_u32 s60, s48, 0x40000
	v_lshl_add_u64 v[234:235], s[48:49], 0, v[142:143]
	s_addc_u32 s61, s49, 0
	s_add_i32 s67, s67, s13
	global_load_lds_dwordx4 v[234:235], off
	v_lshl_add_u64 v[236:237], s[60:61], 0, v[146:147]
	s_mov_b32 m0, s67
	v_lshl_add_u64 v[238:239], s[50:51], 0, v[144:145]
	global_load_lds_dwordx4 v[236:237], off
	v_lshl_add_u64 v[236:237], s[60:61], 0, v[142:143]
	s_add_i32 m0, s67, 0x2000
	s_nop 0
	global_load_lds_dwordx4 v[236:237], off
	v_lshl_add_u64 v[236:237], s[50:51], 0, v[148:149]
	s_mov_b32 m0, s25
	s_nop 0
	global_load_lds_dwordx4 v[236:237], off
	s_mov_b32 m0, s30
	s_nop 0
	global_load_lds_dwordx4 v[238:239], off
	s_waitcnt vmcnt(8)
	s_waitcnt lgkmcnt(0)
	s_barrier
	s_waitcnt lgkmcnt(0)
	v_mfma_f32_16x16x32_bf16 v[60:63], v[130:133], v[182:185], 0
	v_mfma_f32_16x16x32_bf16 v[56:59], v[138:141], v[182:185], 0
	v_mfma_f32_16x16x32_bf16 v[44:47], v[130:133], v[204:207], 0
	v_mfma_f32_16x16x32_bf16 v[40:43], v[138:141], v[204:207], 0
	v_mfma_f32_16x16x32_bf16 v[28:31], v[130:133], v[218:221], 0
	v_mfma_f32_16x16x32_bf16 v[24:27], v[138:141], v[218:221], 0
	v_mfma_f32_16x16x32_bf16 v[12:15], v[130:133], v[226:229], 0
	v_mfma_f32_16x16x32_bf16 v[8:11], v[138:141], v[226:229], 0
	v_mfma_f32_16x16x32_bf16 v[60:63], v[134:137], v[188:191], v[60:63]
	v_mfma_f32_16x16x32_bf16 v[56:59], v[162:165], v[188:191], v[56:59]
	v_mfma_f32_16x16x32_bf16 v[44:47], v[134:137], v[214:217], v[44:47]
	v_mfma_f32_16x16x32_bf16 v[40:43], v[162:165], v[214:217], v[40:43]
	v_mfma_f32_16x16x32_bf16 v[28:31], v[134:137], v[222:225], v[28:31]
	v_mfma_f32_16x16x32_bf16 v[24:27], v[162:165], v[222:225], v[24:27]
	v_mfma_f32_16x16x32_bf16 v[12:15], v[134:137], v[230:233], v[12:15]
	v_mfma_f32_16x16x32_bf16 v[8:11], v[162:165], v[230:233], v[8:11]
	v_mfma_f32_16x16x32_bf16 v[52:55], v[166:169], v[182:185], 0
	v_mfma_f32_16x16x32_bf16 v[48:51], v[174:177], v[182:185], 0
	v_mfma_f32_16x16x32_bf16 v[36:39], v[166:169], v[204:207], 0
	v_mfma_f32_16x16x32_bf16 v[32:35], v[174:177], v[204:207], 0
	v_mfma_f32_16x16x32_bf16 v[20:23], v[166:169], v[218:221], 0
	v_mfma_f32_16x16x32_bf16 v[16:19], v[174:177], v[218:221], 0
	v_mfma_f32_16x16x32_bf16 v[4:7], v[166:169], v[226:229], 0
	v_mfma_f32_16x16x32_bf16 v[0:3], v[174:177], v[226:229], 0
	v_mfma_f32_16x16x32_bf16 v[52:55], v[170:173], v[188:191], v[52:55]
	v_mfma_f32_16x16x32_bf16 v[48:51], v[178:181], v[188:191], v[48:51]
	v_mfma_f32_16x16x32_bf16 v[36:39], v[170:173], v[214:217], v[36:39]
	v_mfma_f32_16x16x32_bf16 v[32:35], v[178:181], v[214:217], v[32:35]
	v_mfma_f32_16x16x32_bf16 v[20:23], v[170:173], v[222:225], v[20:23]
	v_mfma_f32_16x16x32_bf16 v[16:19], v[178:181], v[222:225], v[16:19]
	v_mfma_f32_16x16x32_bf16 v[4:7], v[170:173], v[230:233], v[4:7]
	v_mfma_f32_16x16x32_bf16 v[0:3], v[178:181], v[230:233], v[0:3]
	s_barrier
	s_add_i32 s60, 16, 0x18000
	v_add_u32_e32 v80, s60, v186
	s_add_i32 s61, 16, 0x1c000
	ds_read_b128 v[130:133], v80
	ds_read_b128 v[134:137], v80 offset:1024
	ds_read_b128 v[138:141], v80 offset:2048
	ds_read_b128 v[162:165], v80 offset:3072
	v_add_u32_e32 v80, s61, v186
	ds_read_b128 v[166:169], v80
	ds_read_b128 v[170:173], v80 offset:1024
	ds_read_b128 v[174:177], v80 offset:2048
	ds_read_b128 v[178:181], v80 offset:3072
	s_add_u32 s50, s50, 0x40000
	s_addc_u32 s51, s51, 0
	s_mov_b32 m0, s33
	v_lshl_add_u64 v[240:241], s[50:51], 0, v[148:149]
	ds_read_b128 v[182:185], v187 offset:32768
	ds_read_b128 v[188:191], v187 offset:33792
	ds_read_b128 v[204:207], v187 offset:34816
	ds_read_b128 v[214:217], v187 offset:35840
	ds_read_b128 v[218:221], v187 offset:36864
	ds_read_b128 v[222:225], v187 offset:37888
	ds_read_b128 v[226:229], v187 offset:38912
	ds_read_b128 v[230:233], v187 offset:39936
	global_load_lds_dwordx4 v[240:241], off
	v_lshl_add_u64 v[240:241], s[50:51], 0, v[144:145]
	s_mov_b32 m0, s34
	s_nop 0
	global_load_lds_dwordx4 v[240:241], off
	s_waitcnt vmcnt(8)
	s_waitcnt lgkmcnt(0)
	s_barrier
	s_waitcnt lgkmcnt(0)
	v_mfma_f32_16x16x32_bf16 v[126:129], v[130:133], v[182:185], v[126:129]
	v_mfma_f32_16x16x32_bf16 v[122:125], v[138:141], v[182:185], v[122:125]
	v_mfma_f32_16x16x32_bf16 v[110:113], v[130:133], v[204:207], v[110:113]
	v_mfma_f32_16x16x32_bf16 v[106:109], v[138:141], v[204:207], v[106:109]
	v_mfma_f32_16x16x32_bf16 v[94:97], v[130:133], v[218:221], v[94:97]
	v_mfma_f32_16x16x32_bf16 v[90:93], v[138:141], v[218:221], v[90:93]
	v_mfma_f32_16x16x32_bf16 v[76:79], v[130:133], v[226:229], v[76:79]
	v_mfma_f32_16x16x32_bf16 v[72:75], v[138:141], v[226:229], v[72:75]
	v_mfma_f32_16x16x32_bf16 v[126:129], v[134:137], v[188:191], v[126:129]
	v_mfma_f32_16x16x32_bf16 v[122:125], v[162:165], v[188:191], v[122:125]
	v_mfma_f32_16x16x32_bf16 v[110:113], v[134:137], v[214:217], v[110:113]
	v_mfma_f32_16x16x32_bf16 v[106:109], v[162:165], v[214:217], v[106:109]
	v_mfma_f32_16x16x32_bf16 v[94:97], v[134:137], v[222:225], v[94:97]
	v_mfma_f32_16x16x32_bf16 v[90:93], v[162:165], v[222:225], v[90:93]
	v_mfma_f32_16x16x32_bf16 v[76:79], v[134:137], v[230:233], v[76:79]
	v_mfma_f32_16x16x32_bf16 v[72:75], v[162:165], v[230:233], v[72:75]
	v_mfma_f32_16x16x32_bf16 v[118:121], v[166:169], v[182:185], v[118:121]
	v_mfma_f32_16x16x32_bf16 v[114:117], v[174:177], v[182:185], v[114:117]
	v_mfma_f32_16x16x32_bf16 v[102:105], v[166:169], v[204:207], v[102:105]
	v_mfma_f32_16x16x32_bf16 v[98:101], v[174:177], v[204:207], v[98:101]
	v_mfma_f32_16x16x32_bf16 v[86:89], v[166:169], v[218:221], v[86:89]
	v_mfma_f32_16x16x32_bf16 v[82:85], v[174:177], v[218:221], v[82:85]
	v_mfma_f32_16x16x32_bf16 v[68:71], v[166:169], v[226:229], v[68:71]
	v_mfma_f32_16x16x32_bf16 v[64:67], v[174:177], v[226:229], v[64:67]
	v_mfma_f32_16x16x32_bf16 v[118:121], v[170:173], v[188:191], v[118:121]
	v_mfma_f32_16x16x32_bf16 v[114:117], v[178:181], v[188:191], v[114:117]
	v_mfma_f32_16x16x32_bf16 v[102:105], v[170:173], v[214:217], v[102:105]
	v_mfma_f32_16x16x32_bf16 v[98:101], v[178:181], v[214:217], v[98:101]
	v_mfma_f32_16x16x32_bf16 v[86:89], v[170:173], v[222:225], v[86:89]
	v_mfma_f32_16x16x32_bf16 v[82:85], v[178:181], v[222:225], v[82:85]
	v_mfma_f32_16x16x32_bf16 v[68:71], v[170:173], v[230:233], v[68:71]
	v_mfma_f32_16x16x32_bf16 v[64:67], v[178:181], v[230:233], v[64:67]
	s_barrier
	s_add_i32 s50, s60, s13
	v_lshl_add_u64 v[208:209], v[208:209], 0, s[20:21]
	s_mov_b32 m0, s50
	ds_read_b128 v[182:185], v187 offset:49152
	ds_read_b128 v[188:191], v187 offset:50176
	ds_read_b128 v[204:207], v187 offset:51200
	ds_read_b128 v[214:217], v187 offset:52224
	ds_read_b128 v[218:221], v187 offset:53248
	ds_read_b128 v[222:225], v187 offset:54272
	ds_read_b128 v[226:229], v187 offset:55296
	ds_read_b128 v[230:233], v187 offset:56320
	global_load_lds_dwordx4 v[208:209], off
	s_add_i32 m0, s50, 0x2000
	s_add_u32 s48, s48, 0x40080
	v_lshl_add_u64 v[208:209], v[234:235], 0, s[20:21]
	s_addc_u32 s49, s49, 0
	s_add_i32 s50, s61, s13
	global_load_lds_dwordx4 v[208:209], off
	v_lshl_add_u64 v[208:209], s[48:49], 0, v[146:147]
	s_mov_b32 m0, s50
	s_nop 0
	global_load_lds_dwordx4 v[208:209], off
	v_lshl_add_u64 v[208:209], s[48:49], 0, v[142:143]
	s_add_i32 m0, s50, 0x2000
	s_nop 0
	global_load_lds_dwordx4 v[208:209], off
	v_lshl_add_u64 v[208:209], v[236:237], 0, s[20:21]
	s_mov_b32 m0, s36
	s_nop 0
	global_load_lds_dwordx4 v[208:209], off
	v_lshl_add_u64 v[208:209], v[238:239], 0, s[20:21]
	s_mov_b32 m0, s37
	s_nop 0
	global_load_lds_dwordx4 v[208:209], off
	s_waitcnt vmcnt(8)
	s_waitcnt lgkmcnt(0)
	s_barrier
	s_waitcnt lgkmcnt(0)
	v_mfma_f32_16x16x32_bf16 v[60:63], v[130:133], v[182:185], v[60:63]
	v_mfma_f32_16x16x32_bf16 v[56:59], v[138:141], v[182:185], v[56:59]
	v_mfma_f32_16x16x32_bf16 v[44:47], v[130:133], v[204:207], v[44:47]
	v_mfma_f32_16x16x32_bf16 v[40:43], v[138:141], v[204:207], v[40:43]
	v_mfma_f32_16x16x32_bf16 v[28:31], v[130:133], v[218:221], v[28:31]
	v_mfma_f32_16x16x32_bf16 v[24:27], v[138:141], v[218:221], v[24:27]
	v_mfma_f32_16x16x32_bf16 v[12:15], v[130:133], v[226:229], v[12:15]
	v_mfma_f32_16x16x32_bf16 v[8:11], v[138:141], v[226:229], v[8:11]
	v_mfma_f32_16x16x32_bf16 v[60:63], v[134:137], v[188:191], v[60:63]
	v_mfma_f32_16x16x32_bf16 v[56:59], v[162:165], v[188:191], v[56:59]
	v_mfma_f32_16x16x32_bf16 v[44:47], v[134:137], v[214:217], v[44:47]
	v_mfma_f32_16x16x32_bf16 v[40:43], v[162:165], v[214:217], v[40:43]
	v_mfma_f32_16x16x32_bf16 v[28:31], v[134:137], v[222:225], v[28:31]
	v_mfma_f32_16x16x32_bf16 v[24:27], v[162:165], v[222:225], v[24:27]
	v_mfma_f32_16x16x32_bf16 v[12:15], v[134:137], v[230:233], v[12:15]
	v_mfma_f32_16x16x32_bf16 v[8:11], v[162:165], v[230:233], v[8:11]
	v_mfma_f32_16x16x32_bf16 v[52:55], v[166:169], v[182:185], v[52:55]
	v_mfma_f32_16x16x32_bf16 v[48:51], v[174:177], v[182:185], v[48:51]
	v_mfma_f32_16x16x32_bf16 v[36:39], v[166:169], v[204:207], v[36:39]
	v_mfma_f32_16x16x32_bf16 v[32:35], v[174:177], v[204:207], v[32:35]
	v_mfma_f32_16x16x32_bf16 v[20:23], v[166:169], v[218:221], v[20:23]
	v_mfma_f32_16x16x32_bf16 v[16:19], v[174:177], v[218:221], v[16:19]
	v_mfma_f32_16x16x32_bf16 v[4:7], v[166:169], v[226:229], v[4:7]
	v_mfma_f32_16x16x32_bf16 v[0:3], v[174:177], v[226:229], v[0:3]
	v_mfma_f32_16x16x32_bf16 v[52:55], v[170:173], v[188:191], v[52:55]
	v_mfma_f32_16x16x32_bf16 v[48:51], v[178:181], v[188:191], v[48:51]
	v_mfma_f32_16x16x32_bf16 v[36:39], v[170:173], v[214:217], v[36:39]
	v_mfma_f32_16x16x32_bf16 v[32:35], v[178:181], v[214:217], v[32:35]
	v_mfma_f32_16x16x32_bf16 v[20:23], v[170:173], v[222:225], v[20:23]
	v_mfma_f32_16x16x32_bf16 v[16:19], v[178:181], v[222:225], v[16:19]
	v_mfma_f32_16x16x32_bf16 v[4:7], v[170:173], v[230:233], v[4:7]
	v_mfma_f32_16x16x32_bf16 v[0:3], v[178:181], v[230:233], v[0:3]
	s_barrier
	s_add_i32 s57, s57, 2
	s_add_u32 s46, s46, 0x100
	s_addc_u32 s47, s47, 0
	s_add_u32 s55, s55, 0x100
	s_addc_u32 s56, s56, 0
	s_cmp_gt_u32 s57, 13

.LBB0_639:
	s_add_u32 s54, s46, 0x100
	s_addc_u32 s55, s47, 0
	s_mov_b32 s56, -2
	s_waitcnt lgkmcnt(0)
	s_add_u32 s44, s42, 0x100
	s_addc_u32 s45, s43, 0
	s_add_i32 s57, 16, 0x10000
	s_cmp_eq_u32 s56, 40
	s_cselect_b32 s49, s11, s45
	s_cselect_b32 s48, s10, s44
	v_add_u32_e32 v80, s57, v144
	s_cselect_b32 s47, s15, s55
	s_cselect_b32 s46, s14, s54
	s_add_i32 s60, 16, 0x14000
	ds_read_b128 v[146:149], v80
	ds_read_b128 v[160:163], v80 offset:1024
	ds_read_b128 v[164:167], v80 offset:2048
	ds_read_b128 v[168:171], v80 offset:3072
	v_add_u32_e32 v80, s60, v144
	ds_read_b128 v[172:175], v80
	ds_read_b128 v[176:179], v80 offset:1024
	ds_read_b128 v[180:183], v80 offset:2048
	ds_read_b128 v[184:187], v80 offset:3072
	v_lshl_add_u64 v[142:143], s[42:43], 0, v[138:139]
	s_add_i32 m0, s13, 0xc000
	ds_read_b128 v[188:191], v145
	ds_read_b128 v[204:207], v145 offset:1024
	ds_read_b128 v[214:217], v145 offset:2048
	ds_read_b128 v[218:221], v145 offset:3072
	ds_read_b128 v[222:225], v145 offset:4096
	ds_read_b128 v[226:229], v145 offset:5120
	ds_read_b128 v[230:233], v145 offset:6144
	ds_read_b128 v[234:237], v145 offset:7168
	global_load_lds_dwordx4 v[142:143], off
	v_lshl_add_u64 v[142:143], s[42:43], 0, v[140:141]
	s_add_i32 m0, s13, 0xe000
	s_nop 0
	global_load_lds_dwordx4 v[142:143], off
	s_waitcnt vmcnt(8)
	s_waitcnt lgkmcnt(0)
	s_barrier
	s_waitcnt lgkmcnt(0)
	v_mfma_f32_16x16x32_bf16 v[126:129], v[146:149], v[188:191], 0
	v_mfma_f32_16x16x32_bf16 v[122:125], v[164:167], v[188:191], 0
	v_mfma_f32_16x16x32_bf16 v[110:113], v[146:149], v[214:217], 0
	v_mfma_f32_16x16x32_bf16 v[106:109], v[164:167], v[214:217], 0
	v_mfma_f32_16x16x32_bf16 v[94:97], v[146:149], v[222:225], 0
	v_mfma_f32_16x16x32_bf16 v[90:93], v[164:167], v[222:225], 0
	v_mfma_f32_16x16x32_bf16 v[76:79], v[146:149], v[230:233], 0
	v_mfma_f32_16x16x32_bf16 v[72:75], v[164:167], v[230:233], 0
	v_mfma_f32_16x16x32_bf16 v[126:129], v[160:163], v[204:207], v[126:129]
	v_mfma_f32_16x16x32_bf16 v[122:125], v[168:171], v[204:207], v[122:125]
	v_mfma_f32_16x16x32_bf16 v[110:113], v[160:163], v[218:221], v[110:113]
	v_mfma_f32_16x16x32_bf16 v[106:109], v[168:171], v[218:221], v[106:109]
	v_mfma_f32_16x16x32_bf16 v[94:97], v[160:163], v[226:229], v[94:97]
	v_mfma_f32_16x16x32_bf16 v[90:93], v[168:171], v[226:229], v[90:93]
	v_mfma_f32_16x16x32_bf16 v[76:79], v[160:163], v[234:237], v[76:79]
	v_mfma_f32_16x16x32_bf16 v[72:75], v[168:171], v[234:237], v[72:75]
	v_mfma_f32_16x16x32_bf16 v[118:121], v[172:175], v[188:191], 0
	v_mfma_f32_16x16x32_bf16 v[114:117], v[180:183], v[188:191], 0
	v_mfma_f32_16x16x32_bf16 v[102:105], v[172:175], v[214:217], 0
	v_mfma_f32_16x16x32_bf16 v[98:101], v[180:183], v[214:217], 0
	v_mfma_f32_16x16x32_bf16 v[86:89], v[172:175], v[222:225], 0
	v_mfma_f32_16x16x32_bf16 v[82:85], v[180:183], v[222:225], 0
	v_mfma_f32_16x16x32_bf16 v[68:71], v[172:175], v[230:233], 0
	v_mfma_f32_16x16x32_bf16 v[64:67], v[180:183], v[230:233], 0
	v_mfma_f32_16x16x32_bf16 v[118:121], v[176:179], v[204:207], v[118:121]
	v_mfma_f32_16x16x32_bf16 v[114:117], v[184:187], v[204:207], v[114:117]
	v_mfma_f32_16x16x32_bf16 v[102:105], v[176:179], v[218:221], v[102:105]
	v_mfma_f32_16x16x32_bf16 v[98:101], v[184:187], v[218:221], v[98:101]
	v_mfma_f32_16x16x32_bf16 v[86:89], v[176:179], v[226:229], v[86:89]
	v_mfma_f32_16x16x32_bf16 v[82:85], v[184:187], v[226:229], v[82:85]
	v_mfma_f32_16x16x32_bf16 v[68:71], v[176:179], v[234:237], v[68:71]
	v_mfma_f32_16x16x32_bf16 v[64:67], v[184:187], v[234:237], v[64:67]
	s_barrier
	s_add_i32 s42, s57, s4
	v_lshl_add_u64 v[142:143], s[46:47], 0, v[134:135]
	s_mov_b32 m0, s42
	ds_read_b128 v[188:191], v145 offset:16384
	ds_read_b128 v[204:207], v145 offset:17408
	ds_read_b128 v[214:217], v145 offset:18432
	ds_read_b128 v[218:221], v145 offset:19456
	ds_read_b128 v[222:225], v145 offset:20480
	ds_read_b128 v[226:229], v145 offset:21504
	ds_read_b128 v[230:233], v145 offset:22528
	ds_read_b128 v[234:237], v145 offset:23552
	global_load_lds_dwordx4 v[142:143], off
	s_add_i32 m0, s42, 0x2000
	s_add_u32 s42, s46, 0xb0000
	v_lshl_add_u64 v[150:151], s[46:47], 0, v[130:131]
	s_addc_u32 s43, s47, 0
	s_add_i32 s57, s60, s4
	global_load_lds_dwordx4 v[150:151], off
	v_lshl_add_u64 v[208:209], s[42:43], 0, v[134:135]
	s_mov_b32 m0, s57
	v_lshl_add_u64 v[238:239], s[48:49], 0, v[132:133]
	global_load_lds_dwordx4 v[208:209], off
	v_lshl_add_u64 v[208:209], s[42:43], 0, v[130:131]
	s_add_i32 m0, s57, 0x2000
	s_nop 0
	global_load_lds_dwordx4 v[208:209], off
	v_lshl_add_u64 v[208:209], s[48:49], 0, v[136:137]
	s_mov_b32 m0, s13
	s_nop 0
	global_load_lds_dwordx4 v[208:209], off
	s_mov_b32 m0, s25
	s_nop 0
	global_load_lds_dwordx4 v[238:239], off
	s_waitcnt vmcnt(8)
	s_waitcnt lgkmcnt(0)
	s_barrier
	s_waitcnt lgkmcnt(0)
	v_mfma_f32_16x16x32_bf16 v[60:63], v[146:149], v[188:191], 0
	v_mfma_f32_16x16x32_bf16 v[56:59], v[164:167], v[188:191], 0
	v_mfma_f32_16x16x32_bf16 v[44:47], v[146:149], v[214:217], 0
	v_mfma_f32_16x16x32_bf16 v[40:43], v[164:167], v[214:217], 0
	v_mfma_f32_16x16x32_bf16 v[28:31], v[146:149], v[222:225], 0
	v_mfma_f32_16x16x32_bf16 v[24:27], v[164:167], v[222:225], 0
	v_mfma_f32_16x16x32_bf16 v[12:15], v[146:149], v[230:233], 0
	v_mfma_f32_16x16x32_bf16 v[8:11], v[164:167], v[230:233], 0
	v_mfma_f32_16x16x32_bf16 v[60:63], v[160:163], v[204:207], v[60:63]
	v_mfma_f32_16x16x32_bf16 v[56:59], v[168:171], v[204:207], v[56:59]
	v_mfma_f32_16x16x32_bf16 v[44:47], v[160:163], v[218:221], v[44:47]
	v_mfma_f32_16x16x32_bf16 v[40:43], v[168:171], v[218:221], v[40:43]
	v_mfma_f32_16x16x32_bf16 v[28:31], v[160:163], v[226:229], v[28:31]
	v_mfma_f32_16x16x32_bf16 v[24:27], v[168:171], v[226:229], v[24:27]
	v_mfma_f32_16x16x32_bf16 v[12:15], v[160:163], v[234:237], v[12:15]
	v_mfma_f32_16x16x32_bf16 v[8:11], v[168:171], v[234:237], v[8:11]
	v_mfma_f32_16x16x32_bf16 v[52:55], v[172:175], v[188:191], 0
	v_mfma_f32_16x16x32_bf16 v[48:51], v[180:183], v[188:191], 0
	v_mfma_f32_16x16x32_bf16 v[36:39], v[172:175], v[214:217], 0
	v_mfma_f32_16x16x32_bf16 v[32:35], v[180:183], v[214:217], 0
	v_mfma_f32_16x16x32_bf16 v[20:23], v[172:175], v[222:225], 0
	v_mfma_f32_16x16x32_bf16 v[16:19], v[180:183], v[222:225], 0
	v_mfma_f32_16x16x32_bf16 v[4:7], v[172:175], v[230:233], 0
	v_mfma_f32_16x16x32_bf16 v[0:3], v[180:183], v[230:233], 0
	v_mfma_f32_16x16x32_bf16 v[52:55], v[176:179], v[204:207], v[52:55]
	v_mfma_f32_16x16x32_bf16 v[48:51], v[184:187], v[204:207], v[48:51]
	v_mfma_f32_16x16x32_bf16 v[36:39], v[176:179], v[218:221], v[36:39]
	v_mfma_f32_16x16x32_bf16 v[32:35], v[184:187], v[218:221], v[32:35]
	v_mfma_f32_16x16x32_bf16 v[20:23], v[176:179], v[226:229], v[20:23]
	v_mfma_f32_16x16x32_bf16 v[16:19], v[184:187], v[226:229], v[16:19]
	v_mfma_f32_16x16x32_bf16 v[4:7], v[176:179], v[234:237], v[4:7]
	v_mfma_f32_16x16x32_bf16 v[0:3], v[184:187], v[234:237], v[0:3]
	s_barrier
	s_add_i32 s57, 16, 0x18000
	v_add_u32_e32 v80, s57, v144
	s_add_i32 s60, 16, 0x1c000
	ds_read_b128 v[146:149], v80
	ds_read_b128 v[160:163], v80 offset:1024
	ds_read_b128 v[164:167], v80 offset:2048
	ds_read_b128 v[168:171], v80 offset:3072
	v_add_u32_e32 v80, s60, v144
	ds_read_b128 v[172:175], v80
	ds_read_b128 v[176:179], v80 offset:1024
	ds_read_b128 v[180:183], v80 offset:2048
	ds_read_b128 v[184:187], v80 offset:3072
	s_add_u32 s42, s48, 0xb0000
	s_addc_u32 s43, s49, 0
	s_mov_b32 m0, s30
	v_lshl_add_u64 v[240:241], s[42:43], 0, v[136:137]
	ds_read_b128 v[188:191], v145 offset:32768
	ds_read_b128 v[204:207], v145 offset:33792
	ds_read_b128 v[214:217], v145 offset:34816
	ds_read_b128 v[218:221], v145 offset:35840
	ds_read_b128 v[222:225], v145 offset:36864
	ds_read_b128 v[226:229], v145 offset:37888
	ds_read_b128 v[230:233], v145 offset:38912
	ds_read_b128 v[234:237], v145 offset:39936
	global_load_lds_dwordx4 v[240:241], off
	v_lshl_add_u64 v[240:241], s[42:43], 0, v[132:133]
	s_mov_b32 m0, s33
	s_nop 0
	global_load_lds_dwordx4 v[240:241], off
	s_waitcnt vmcnt(8)
	s_waitcnt lgkmcnt(0)
	s_barrier
	s_waitcnt lgkmcnt(0)
	v_mfma_f32_16x16x32_bf16 v[126:129], v[146:149], v[188:191], v[126:129]
	v_mfma_f32_16x16x32_bf16 v[122:125], v[164:167], v[188:191], v[122:125]
	v_mfma_f32_16x16x32_bf16 v[110:113], v[146:149], v[214:217], v[110:113]
	v_mfma_f32_16x16x32_bf16 v[106:109], v[164:167], v[214:217], v[106:109]
	v_mfma_f32_16x16x32_bf16 v[94:97], v[146:149], v[222:225], v[94:97]
	v_mfma_f32_16x16x32_bf16 v[90:93], v[164:167], v[222:225], v[90:93]
	v_mfma_f32_16x16x32_bf16 v[76:79], v[146:149], v[230:233], v[76:79]
	v_mfma_f32_16x16x32_bf16 v[72:75], v[164:167], v[230:233], v[72:75]
	v_mfma_f32_16x16x32_bf16 v[126:129], v[160:163], v[204:207], v[126:129]
	v_mfma_f32_16x16x32_bf16 v[122:125], v[168:171], v[204:207], v[122:125]
	v_mfma_f32_16x16x32_bf16 v[110:113], v[160:163], v[218:221], v[110:113]
	v_mfma_f32_16x16x32_bf16 v[106:109], v[168:171], v[218:221], v[106:109]
	v_mfma_f32_16x16x32_bf16 v[94:97], v[160:163], v[226:229], v[94:97]
	v_mfma_f32_16x16x32_bf16 v[90:93], v[168:171], v[226:229], v[90:93]
	v_mfma_f32_16x16x32_bf16 v[76:79], v[160:163], v[234:237], v[76:79]
	v_mfma_f32_16x16x32_bf16 v[72:75], v[168:171], v[234:237], v[72:75]
	v_mfma_f32_16x16x32_bf16 v[118:121], v[172:175], v[188:191], v[118:121]
	v_mfma_f32_16x16x32_bf16 v[114:117], v[180:183], v[188:191], v[114:117]
	v_mfma_f32_16x16x32_bf16 v[102:105], v[172:175], v[214:217], v[102:105]
	v_mfma_f32_16x16x32_bf16 v[98:101], v[180:183], v[214:217], v[98:101]
	v_mfma_f32_16x16x32_bf16 v[86:89], v[172:175], v[222:225], v[86:89]
	v_mfma_f32_16x16x32_bf16 v[82:85], v[180:183], v[222:225], v[82:85]
	v_mfma_f32_16x16x32_bf16 v[68:71], v[172:175], v[230:233], v[68:71]
	v_mfma_f32_16x16x32_bf16 v[64:67], v[180:183], v[230:233], v[64:67]
	v_mfma_f32_16x16x32_bf16 v[118:121], v[176:179], v[204:207], v[118:121]
	v_mfma_f32_16x16x32_bf16 v[114:117], v[184:187], v[204:207], v[114:117]
	v_mfma_f32_16x16x32_bf16 v[102:105], v[176:179], v[218:221], v[102:105]
	v_mfma_f32_16x16x32_bf16 v[98:101], v[184:187], v[218:221], v[98:101]
	v_mfma_f32_16x16x32_bf16 v[86:89], v[176:179], v[226:229], v[86:89]
	v_mfma_f32_16x16x32_bf16 v[82:85], v[184:187], v[226:229], v[82:85]
	v_mfma_f32_16x16x32_bf16 v[68:71], v[176:179], v[234:237], v[68:71]
	v_mfma_f32_16x16x32_bf16 v[64:67], v[184:187], v[234:237], v[64:67]
	s_barrier
	s_add_i32 s42, s57, s4
	v_lshl_add_u64 v[142:143], v[142:143], 0, s[20:21]
	s_mov_b32 m0, s42
	ds_read_b128 v[188:191], v145 offset:49152
	ds_read_b128 v[204:207], v145 offset:50176
	ds_read_b128 v[214:217], v145 offset:51200
	ds_read_b128 v[218:221], v145 offset:52224
	ds_read_b128 v[222:225], v145 offset:53248
	ds_read_b128 v[226:229], v145 offset:54272
	ds_read_b128 v[230:233], v145 offset:55296
	ds_read_b128 v[234:237], v145 offset:56320
	global_load_lds_dwordx4 v[142:143], off
	s_add_i32 m0, s42, 0x2000
	s_add_u32 s42, s46, 0xb0080
	v_lshl_add_u64 v[142:143], v[150:151], 0, s[20:21]
	s_addc_u32 s43, s47, 0
	s_add_i32 s46, s60, s4
	global_load_lds_dwordx4 v[142:143], off
	v_lshl_add_u64 v[142:143], s[42:43], 0, v[134:135]
	s_mov_b32 m0, s46
	s_nop 0
	global_load_lds_dwordx4 v[142:143], off
	v_lshl_add_u64 v[142:143], s[42:43], 0, v[130:131]
	s_add_i32 m0, s46, 0x2000
	s_nop 0
	global_load_lds_dwordx4 v[142:143], off
	v_lshl_add_u64 v[142:143], v[208:209], 0, s[20:21]
	s_mov_b32 m0, s34
	s_nop 0
	global_load_lds_dwordx4 v[142:143], off
	v_lshl_add_u64 v[142:143], v[238:239], 0, s[20:21]
	s_mov_b32 m0, s36
	s_nop 0
	global_load_lds_dwordx4 v[142:143], off
	s_waitcnt vmcnt(8)
	s_waitcnt lgkmcnt(0)
	s_barrier
	s_waitcnt lgkmcnt(0)
	v_mfma_f32_16x16x32_bf16 v[60:63], v[146:149], v[188:191], v[60:63]
	v_mfma_f32_16x16x32_bf16 v[56:59], v[164:167], v[188:191], v[56:59]
	v_mfma_f32_16x16x32_bf16 v[44:47], v[146:149], v[214:217], v[44:47]
	v_mfma_f32_16x16x32_bf16 v[40:43], v[164:167], v[214:217], v[40:43]
	v_mfma_f32_16x16x32_bf16 v[28:31], v[146:149], v[222:225], v[28:31]
	v_mfma_f32_16x16x32_bf16 v[24:27], v[164:167], v[222:225], v[24:27]
	v_mfma_f32_16x16x32_bf16 v[12:15], v[146:149], v[230:233], v[12:15]
	v_mfma_f32_16x16x32_bf16 v[8:11], v[164:167], v[230:233], v[8:11]
	v_mfma_f32_16x16x32_bf16 v[60:63], v[160:163], v[204:207], v[60:63]
	v_mfma_f32_16x16x32_bf16 v[56:59], v[168:171], v[204:207], v[56:59]
	v_mfma_f32_16x16x32_bf16 v[44:47], v[160:163], v[218:221], v[44:47]
	v_mfma_f32_16x16x32_bf16 v[40:43], v[168:171], v[218:221], v[40:43]
	v_mfma_f32_16x16x32_bf16 v[28:31], v[160:163], v[226:229], v[28:31]
	v_mfma_f32_16x16x32_bf16 v[24:27], v[168:171], v[226:229], v[24:27]
	v_mfma_f32_16x16x32_bf16 v[12:15], v[160:163], v[234:237], v[12:15]
	v_mfma_f32_16x16x32_bf16 v[8:11], v[168:171], v[234:237], v[8:11]
	v_mfma_f32_16x16x32_bf16 v[52:55], v[172:175], v[188:191], v[52:55]
	v_mfma_f32_16x16x32_bf16 v[48:51], v[180:183], v[188:191], v[48:51]
	v_mfma_f32_16x16x32_bf16 v[36:39], v[172:175], v[214:217], v[36:39]
	v_mfma_f32_16x16x32_bf16 v[32:35], v[180:183], v[214:217], v[32:35]
	v_mfma_f32_16x16x32_bf16 v[20:23], v[172:175], v[222:225], v[20:23]
	v_mfma_f32_16x16x32_bf16 v[16:19], v[180:183], v[222:225], v[16:19]
	v_mfma_f32_16x16x32_bf16 v[4:7], v[172:175], v[230:233], v[4:7]
	v_mfma_f32_16x16x32_bf16 v[0:3], v[180:183], v[230:233], v[0:3]
	v_mfma_f32_16x16x32_bf16 v[52:55], v[176:179], v[204:207], v[52:55]
	v_mfma_f32_16x16x32_bf16 v[48:51], v[184:187], v[204:207], v[48:51]
	v_mfma_f32_16x16x32_bf16 v[36:39], v[176:179], v[218:221], v[36:39]
	v_mfma_f32_16x16x32_bf16 v[32:35], v[184:187], v[218:221], v[32:35]
	v_mfma_f32_16x16x32_bf16 v[20:23], v[176:179], v[226:229], v[20:23]
	v_mfma_f32_16x16x32_bf16 v[16:19], v[184:187], v[226:229], v[16:19]
	v_mfma_f32_16x16x32_bf16 v[4:7], v[176:179], v[234:237], v[4:7]
	v_mfma_f32_16x16x32_bf16 v[0:3], v[184:187], v[234:237], v[0:3]
	s_barrier
	s_add_i32 s56, s56, 2
	s_add_u32 s54, s54, 0x100
	s_addc_u32 s55, s55, 0
	s_cmp_gt_u32 s56, 41
	s_mov_b64 s[42:43], s[44:45]

.LBB0_676:
	s_ashr_i32 s15, s14, 31
	s_lshl_b64 s[42:43], s[14:15], 19
	s_add_u32 s42, s38, s42
	s_addc_u32 s43, s39, s43
	s_and_b64 s[44:45], s[40:41], exec
	s_cselect_b32 s15, s43, s47
	s_cselect_b32 s54, s42, s46
	s_ashr_i32 s11, s10, 31
	s_lshl_b64 s[44:45], s[10:11], 19
	v_readlane_b32 s11, v253, 33
	s_add_u32 s44, s11, s44
	v_readlane_b32 s11, v253, 34
	s_addc_u32 s45, s11, s45
	s_and_b64 s[50:51], s[40:41], exec
	s_cselect_b32 s11, s45, s49
	s_cselect_b32 s55, s44, s48
	s_add_u32 s46, s46, 0x40080
	s_addc_u32 s47, s47, 0
	s_add_u32 s56, s48, 0x100
	s_addc_u32 s57, s49, 0
	s_mov_b32 s60, -2
	s_add_u32 s48, s46, 0xfffc0080
	s_addc_u32 s49, s47, -1
	s_add_i32 s61, 16, 0x10000
	s_cmp_eq_u32 s60, 12
	s_cselect_b32 s51, s15, s49
	s_cselect_b32 s50, s54, s48
	v_add_u32_e32 v80, s61, v146
	s_cselect_b32 s49, s11, s57
	s_cselect_b32 s48, s55, s56
	s_add_i32 s74, 16, 0x14000
	ds_read_b128 v[142:145], v80
	ds_read_b128 v[148:151], v80 offset:1024
	ds_read_b128 v[160:163], v80 offset:2048
	ds_read_b128 v[164:167], v80 offset:3072
	v_add_u32_e32 v80, s74, v146
	ds_read_b128 v[168:171], v80
	ds_read_b128 v[172:175], v80 offset:1024
	ds_read_b128 v[176:179], v80 offset:2048
	ds_read_b128 v[180:183], v80 offset:3072
	v_lshl_add_u64 v[208:209], s[46:47], 0, v[138:139]
	s_add_i32 m0, s13, 0xc000
	ds_read_b128 v[184:187], v147
	ds_read_b128 v[188:191], v147 offset:1024
	ds_read_b128 v[204:207], v147 offset:2048
	ds_read_b128 v[214:217], v147 offset:3072
	ds_read_b128 v[218:221], v147 offset:4096
	ds_read_b128 v[222:225], v147 offset:5120
	ds_read_b128 v[226:229], v147 offset:6144
	ds_read_b128 v[230:233], v147 offset:7168
	global_load_lds_dwordx4 v[208:209], off
	v_lshl_add_u64 v[208:209], s[46:47], 0, v[140:141]
	s_add_i32 m0, s13, 0xe000
	s_nop 0
	global_load_lds_dwordx4 v[208:209], off
	s_waitcnt vmcnt(8)
	s_waitcnt lgkmcnt(0)
	s_barrier
	s_waitcnt lgkmcnt(0)
	v_mfma_f32_16x16x32_bf16 v[126:129], v[142:145], v[184:187], 0
	v_mfma_f32_16x16x32_bf16 v[118:121], v[160:163], v[184:187], 0
	v_mfma_f32_16x16x32_bf16 v[110:113], v[142:145], v[204:207], 0
	v_mfma_f32_16x16x32_bf16 v[102:105], v[160:163], v[204:207], 0
	v_mfma_f32_16x16x32_bf16 v[94:97], v[142:145], v[218:221], 0
	v_mfma_f32_16x16x32_bf16 v[86:89], v[160:163], v[218:221], 0
	v_mfma_f32_16x16x32_bf16 v[76:79], v[142:145], v[226:229], 0
	v_mfma_f32_16x16x32_bf16 v[68:71], v[160:163], v[226:229], 0
	v_mfma_f32_16x16x32_bf16 v[126:129], v[148:151], v[188:191], v[126:129]
	v_mfma_f32_16x16x32_bf16 v[118:121], v[164:167], v[188:191], v[118:121]
	v_mfma_f32_16x16x32_bf16 v[110:113], v[148:151], v[214:217], v[110:113]
	v_mfma_f32_16x16x32_bf16 v[102:105], v[164:167], v[214:217], v[102:105]
	v_mfma_f32_16x16x32_bf16 v[94:97], v[148:151], v[222:225], v[94:97]
	v_mfma_f32_16x16x32_bf16 v[86:89], v[164:167], v[222:225], v[86:89]
	v_mfma_f32_16x16x32_bf16 v[76:79], v[148:151], v[230:233], v[76:79]
	v_mfma_f32_16x16x32_bf16 v[68:71], v[164:167], v[230:233], v[68:71]
	v_mfma_f32_16x16x32_bf16 v[122:125], v[168:171], v[184:187], 0
	v_mfma_f32_16x16x32_bf16 v[114:117], v[176:179], v[184:187], 0
	v_mfma_f32_16x16x32_bf16 v[106:109], v[168:171], v[204:207], 0
	v_mfma_f32_16x16x32_bf16 v[98:101], v[176:179], v[204:207], 0
	v_mfma_f32_16x16x32_bf16 v[90:93], v[168:171], v[218:221], 0
	v_mfma_f32_16x16x32_bf16 v[82:85], v[176:179], v[218:221], 0
	v_mfma_f32_16x16x32_bf16 v[72:75], v[168:171], v[226:229], 0
	v_mfma_f32_16x16x32_bf16 v[64:67], v[176:179], v[226:229], 0
	v_mfma_f32_16x16x32_bf16 v[122:125], v[172:175], v[188:191], v[122:125]
	v_mfma_f32_16x16x32_bf16 v[114:117], v[180:183], v[188:191], v[114:117]
	v_mfma_f32_16x16x32_bf16 v[106:109], v[172:175], v[214:217], v[106:109]
	v_mfma_f32_16x16x32_bf16 v[98:101], v[180:183], v[214:217], v[98:101]
	v_mfma_f32_16x16x32_bf16 v[90:93], v[172:175], v[222:225], v[90:93]
	v_mfma_f32_16x16x32_bf16 v[82:85], v[180:183], v[222:225], v[82:85]
	v_mfma_f32_16x16x32_bf16 v[72:75], v[172:175], v[230:233], v[72:75]
	v_mfma_f32_16x16x32_bf16 v[64:67], v[180:183], v[230:233], v[64:67]
	s_barrier
	s_add_i32 s61, s61, s4
	v_lshl_add_u64 v[208:209], s[48:49], 0, v[134:135]
	s_mov_b32 m0, s61
	ds_read_b128 v[184:187], v147 offset:16384
	ds_read_b128 v[188:191], v147 offset:17408
	ds_read_b128 v[204:207], v147 offset:18432
	ds_read_b128 v[214:217], v147 offset:19456
	ds_read_b128 v[218:221], v147 offset:20480
	ds_read_b128 v[222:225], v147 offset:21504
	ds_read_b128 v[226:229], v147 offset:22528
	ds_read_b128 v[230:233], v147 offset:23552
	global_load_lds_dwordx4 v[208:209], off
	s_add_i32 m0, s61, 0x2000
	s_add_u32 s66, s48, 0x40000
	v_lshl_add_u64 v[234:235], s[48:49], 0, v[130:131]
	s_addc_u32 s67, s49, 0
	s_add_i32 s61, s74, s4
	global_load_lds_dwordx4 v[234:235], off
	v_lshl_add_u64 v[236:237], s[66:67], 0, v[134:135]
	s_mov_b32 m0, s61
	v_lshl_add_u64 v[238:239], s[50:51], 0, v[132:133]
	global_load_lds_dwordx4 v[236:237], off
	v_lshl_add_u64 v[236:237], s[66:67], 0, v[130:131]
	s_add_i32 m0, s61, 0x2000
	s_nop 0
	global_load_lds_dwordx4 v[236:237], off
	v_lshl_add_u64 v[236:237], s[50:51], 0, v[136:137]
	s_mov_b32 m0, s13
	s_nop 0
	global_load_lds_dwordx4 v[236:237], off
	s_mov_b32 m0, s25
	s_nop 0
	global_load_lds_dwordx4 v[238:239], off
	s_waitcnt vmcnt(8)
	s_waitcnt lgkmcnt(0)
	s_barrier
	s_waitcnt lgkmcnt(0)
	v_mfma_f32_16x16x32_bf16 v[60:63], v[142:145], v[184:187], 0
	v_mfma_f32_16x16x32_bf16 v[52:55], v[160:163], v[184:187], 0
	v_mfma_f32_16x16x32_bf16 v[44:47], v[142:145], v[204:207], 0
	v_mfma_f32_16x16x32_bf16 v[36:39], v[160:163], v[204:207], 0
	v_mfma_f32_16x16x32_bf16 v[28:31], v[142:145], v[218:221], 0
	v_mfma_f32_16x16x32_bf16 v[20:23], v[160:163], v[218:221], 0
	v_mfma_f32_16x16x32_bf16 v[12:15], v[142:145], v[226:229], 0
	v_mfma_f32_16x16x32_bf16 v[4:7], v[160:163], v[226:229], 0
	v_mfma_f32_16x16x32_bf16 v[60:63], v[148:151], v[188:191], v[60:63]
	v_mfma_f32_16x16x32_bf16 v[52:55], v[164:167], v[188:191], v[52:55]
	v_mfma_f32_16x16x32_bf16 v[44:47], v[148:151], v[214:217], v[44:47]
	v_mfma_f32_16x16x32_bf16 v[36:39], v[164:167], v[214:217], v[36:39]
	v_mfma_f32_16x16x32_bf16 v[28:31], v[148:151], v[222:225], v[28:31]
	v_mfma_f32_16x16x32_bf16 v[20:23], v[164:167], v[222:225], v[20:23]
	v_mfma_f32_16x16x32_bf16 v[12:15], v[148:151], v[230:233], v[12:15]
	v_mfma_f32_16x16x32_bf16 v[4:7], v[164:167], v[230:233], v[4:7]
	v_mfma_f32_16x16x32_bf16 v[56:59], v[168:171], v[184:187], 0
	v_mfma_f32_16x16x32_bf16 v[48:51], v[176:179], v[184:187], 0
	v_mfma_f32_16x16x32_bf16 v[40:43], v[168:171], v[204:207], 0
	v_mfma_f32_16x16x32_bf16 v[32:35], v[176:179], v[204:207], 0
	v_mfma_f32_16x16x32_bf16 v[24:27], v[168:171], v[218:221], 0
	v_mfma_f32_16x16x32_bf16 v[16:19], v[176:179], v[218:221], 0
	v_mfma_f32_16x16x32_bf16 v[8:11], v[168:171], v[226:229], 0
	v_mfma_f32_16x16x32_bf16 v[0:3], v[176:179], v[226:229], 0
	v_mfma_f32_16x16x32_bf16 v[56:59], v[172:175], v[188:191], v[56:59]
	v_mfma_f32_16x16x32_bf16 v[48:51], v[180:183], v[188:191], v[48:51]
	v_mfma_f32_16x16x32_bf16 v[40:43], v[172:175], v[214:217], v[40:43]
	v_mfma_f32_16x16x32_bf16 v[32:35], v[180:183], v[214:217], v[32:35]
	v_mfma_f32_16x16x32_bf16 v[24:27], v[172:175], v[222:225], v[24:27]
	v_mfma_f32_16x16x32_bf16 v[16:19], v[180:183], v[222:225], v[16:19]
	v_mfma_f32_16x16x32_bf16 v[8:11], v[172:175], v[230:233], v[8:11]
	v_mfma_f32_16x16x32_bf16 v[0:3], v[180:183], v[230:233], v[0:3]
	s_barrier
	s_add_i32 s61, 16, 0x18000
	v_add_u32_e32 v80, s61, v146
	s_add_i32 s66, 16, 0x1c000
	ds_read_b128 v[142:145], v80
	ds_read_b128 v[148:151], v80 offset:1024
	ds_read_b128 v[160:163], v80 offset:2048
	ds_read_b128 v[164:167], v80 offset:3072
	v_add_u32_e32 v80, s66, v146
	ds_read_b128 v[168:171], v80
	ds_read_b128 v[172:175], v80 offset:1024
	ds_read_b128 v[176:179], v80 offset:2048
	ds_read_b128 v[180:183], v80 offset:3072
	s_add_u32 s50, s50, 0x40000
	s_addc_u32 s51, s51, 0
	s_mov_b32 m0, s30
	v_lshl_add_u64 v[240:241], s[50:51], 0, v[136:137]
	ds_read_b128 v[184:187], v147 offset:32768
	ds_read_b128 v[188:191], v147 offset:33792
	ds_read_b128 v[204:207], v147 offset:34816
	ds_read_b128 v[214:217], v147 offset:35840
	ds_read_b128 v[218:221], v147 offset:36864
	ds_read_b128 v[222:225], v147 offset:37888
	ds_read_b128 v[226:229], v147 offset:38912
	ds_read_b128 v[230:233], v147 offset:39936
	global_load_lds_dwordx4 v[240:241], off
	v_lshl_add_u64 v[240:241], s[50:51], 0, v[132:133]
	s_mov_b32 m0, s33
	s_nop 0
	global_load_lds_dwordx4 v[240:241], off
	s_waitcnt vmcnt(8)
	s_waitcnt lgkmcnt(0)
	s_barrier
	s_waitcnt lgkmcnt(0)
	v_mfma_f32_16x16x32_bf16 v[126:129], v[142:145], v[184:187], v[126:129]
	v_mfma_f32_16x16x32_bf16 v[118:121], v[160:163], v[184:187], v[118:121]
	v_mfma_f32_16x16x32_bf16 v[110:113], v[142:145], v[204:207], v[110:113]
	v_mfma_f32_16x16x32_bf16 v[102:105], v[160:163], v[204:207], v[102:105]
	v_mfma_f32_16x16x32_bf16 v[94:97], v[142:145], v[218:221], v[94:97]
	v_mfma_f32_16x16x32_bf16 v[86:89], v[160:163], v[218:221], v[86:89]
	v_mfma_f32_16x16x32_bf16 v[76:79], v[142:145], v[226:229], v[76:79]
	v_mfma_f32_16x16x32_bf16 v[68:71], v[160:163], v[226:229], v[68:71]
	v_mfma_f32_16x16x32_bf16 v[126:129], v[148:151], v[188:191], v[126:129]
	v_mfma_f32_16x16x32_bf16 v[118:121], v[164:167], v[188:191], v[118:121]
	v_mfma_f32_16x16x32_bf16 v[110:113], v[148:151], v[214:217], v[110:113]
	v_mfma_f32_16x16x32_bf16 v[102:105], v[164:167], v[214:217], v[102:105]
	v_mfma_f32_16x16x32_bf16 v[94:97], v[148:151], v[222:225], v[94:97]
	v_mfma_f32_16x16x32_bf16 v[86:89], v[164:167], v[222:225], v[86:89]
	v_mfma_f32_16x16x32_bf16 v[76:79], v[148:151], v[230:233], v[76:79]
	v_mfma_f32_16x16x32_bf16 v[68:71], v[164:167], v[230:233], v[68:71]
	v_mfma_f32_16x16x32_bf16 v[122:125], v[168:171], v[184:187], v[122:125]
	v_mfma_f32_16x16x32_bf16 v[114:117], v[176:179], v[184:187], v[114:117]
	v_mfma_f32_16x16x32_bf16 v[106:109], v[168:171], v[204:207], v[106:109]
	v_mfma_f32_16x16x32_bf16 v[98:101], v[176:179], v[204:207], v[98:101]
	v_mfma_f32_16x16x32_bf16 v[90:93], v[168:171], v[218:221], v[90:93]
	v_mfma_f32_16x16x32_bf16 v[82:85], v[176:179], v[218:221], v[82:85]
	v_mfma_f32_16x16x32_bf16 v[72:75], v[168:171], v[226:229], v[72:75]
	v_mfma_f32_16x16x32_bf16 v[64:67], v[176:179], v[226:229], v[64:67]
	v_mfma_f32_16x16x32_bf16 v[122:125], v[172:175], v[188:191], v[122:125]
	v_mfma_f32_16x16x32_bf16 v[114:117], v[180:183], v[188:191], v[114:117]
	v_mfma_f32_16x16x32_bf16 v[106:109], v[172:175], v[214:217], v[106:109]
	v_mfma_f32_16x16x32_bf16 v[98:101], v[180:183], v[214:217], v[98:101]
	v_mfma_f32_16x16x32_bf16 v[90:93], v[172:175], v[222:225], v[90:93]
	v_mfma_f32_16x16x32_bf16 v[82:85], v[180:183], v[222:225], v[82:85]
	v_mfma_f32_16x16x32_bf16 v[72:75], v[172:175], v[230:233], v[72:75]
	v_mfma_f32_16x16x32_bf16 v[64:67], v[180:183], v[230:233], v[64:67]
	s_barrier
	s_add_i32 s50, s61, s4
	v_lshl_add_u64 v[208:209], v[208:209], 0, s[20:21]
	s_mov_b32 m0, s50
	ds_read_b128 v[184:187], v147 offset:49152
	ds_read_b128 v[188:191], v147 offset:50176
	ds_read_b128 v[204:207], v147 offset:51200
	ds_read_b128 v[214:217], v147 offset:52224
	ds_read_b128 v[218:221], v147 offset:53248
	ds_read_b128 v[222:225], v147 offset:54272
	ds_read_b128 v[226:229], v147 offset:55296
	ds_read_b128 v[230:233], v147 offset:56320
	global_load_lds_dwordx4 v[208:209], off
	s_add_i32 m0, s50, 0x2000
	s_add_u32 s48, s48, 0x40080
	v_lshl_add_u64 v[208:209], v[234:235], 0, s[20:21]
	s_addc_u32 s49, s49, 0
	s_add_i32 s50, s66, s4
	global_load_lds_dwordx4 v[208:209], off
	v_lshl_add_u64 v[208:209], s[48:49], 0, v[134:135]
	s_mov_b32 m0, s50
	s_nop 0
	global_load_lds_dwordx4 v[208:209], off
	v_lshl_add_u64 v[208:209], s[48:49], 0, v[130:131]
	s_add_i32 m0, s50, 0x2000
	s_nop 0
	global_load_lds_dwordx4 v[208:209], off
	v_lshl_add_u64 v[208:209], v[236:237], 0, s[20:21]
	s_mov_b32 m0, s34
	s_nop 0
	global_load_lds_dwordx4 v[208:209], off
	v_lshl_add_u64 v[208:209], v[238:239], 0, s[20:21]
	s_mov_b32 m0, s36
	s_nop 0
	global_load_lds_dwordx4 v[208:209], off
	s_waitcnt vmcnt(8)
	s_waitcnt lgkmcnt(0)
	s_barrier
	s_waitcnt lgkmcnt(0)
	v_mfma_f32_16x16x32_bf16 v[60:63], v[142:145], v[184:187], v[60:63]
	v_mfma_f32_16x16x32_bf16 v[52:55], v[160:163], v[184:187], v[52:55]
	v_mfma_f32_16x16x32_bf16 v[44:47], v[142:145], v[204:207], v[44:47]
	v_mfma_f32_16x16x32_bf16 v[36:39], v[160:163], v[204:207], v[36:39]
	v_mfma_f32_16x16x32_bf16 v[28:31], v[142:145], v[218:221], v[28:31]
	v_mfma_f32_16x16x32_bf16 v[20:23], v[160:163], v[218:221], v[20:23]
	v_mfma_f32_16x16x32_bf16 v[12:15], v[142:145], v[226:229], v[12:15]
	v_mfma_f32_16x16x32_bf16 v[4:7], v[160:163], v[226:229], v[4:7]
	v_mfma_f32_16x16x32_bf16 v[60:63], v[148:151], v[188:191], v[60:63]
	v_mfma_f32_16x16x32_bf16 v[52:55], v[164:167], v[188:191], v[52:55]
	v_mfma_f32_16x16x32_bf16 v[44:47], v[148:151], v[214:217], v[44:47]
	v_mfma_f32_16x16x32_bf16 v[36:39], v[164:167], v[214:217], v[36:39]
	v_mfma_f32_16x16x32_bf16 v[28:31], v[148:151], v[222:225], v[28:31]
	v_mfma_f32_16x16x32_bf16 v[20:23], v[164:167], v[222:225], v[20:23]
	v_mfma_f32_16x16x32_bf16 v[12:15], v[148:151], v[230:233], v[12:15]
	v_mfma_f32_16x16x32_bf16 v[4:7], v[164:167], v[230:233], v[4:7]
	v_mfma_f32_16x16x32_bf16 v[56:59], v[168:171], v[184:187], v[56:59]
	v_mfma_f32_16x16x32_bf16 v[48:51], v[176:179], v[184:187], v[48:51]
	v_mfma_f32_16x16x32_bf16 v[40:43], v[168:171], v[204:207], v[40:43]
	v_mfma_f32_16x16x32_bf16 v[32:35], v[176:179], v[204:207], v[32:35]
	v_mfma_f32_16x16x32_bf16 v[24:27], v[168:171], v[218:221], v[24:27]
	v_mfma_f32_16x16x32_bf16 v[16:19], v[176:179], v[218:221], v[16:19]
	v_mfma_f32_16x16x32_bf16 v[8:11], v[168:171], v[226:229], v[8:11]
	v_mfma_f32_16x16x32_bf16 v[0:3], v[176:179], v[226:229], v[0:3]
	v_mfma_f32_16x16x32_bf16 v[56:59], v[172:175], v[188:191], v[56:59]
	v_mfma_f32_16x16x32_bf16 v[48:51], v[180:183], v[188:191], v[48:51]
	v_mfma_f32_16x16x32_bf16 v[40:43], v[172:175], v[214:217], v[40:43]
	v_mfma_f32_16x16x32_bf16 v[32:35], v[180:183], v[214:217], v[32:35]
	v_mfma_f32_16x16x32_bf16 v[24:27], v[172:175], v[222:225], v[24:27]
	v_mfma_f32_16x16x32_bf16 v[16:19], v[180:183], v[222:225], v[16:19]
	v_mfma_f32_16x16x32_bf16 v[8:11], v[172:175], v[230:233], v[8:11]
	v_mfma_f32_16x16x32_bf16 v[0:3], v[180:183], v[230:233], v[0:3]
	s_barrier
	s_add_i32 s60, s60, 2
	s_add_u32 s46, s46, 0x100
	s_addc_u32 s47, s47, 0
	s_add_u32 s56, s56, 0x100
	s_addc_u32 s57, s57, 0
	s_cmp_gt_u32 s60, 13
